# Conformer conv phase hand-written: LDS-transpose LayerNorm statistics instead of 32-value wave butterfly
# speedup vs baseline: 1.0131x; 1.0110x over previous
.LBB0_544:
	v_readlane_b32 s8, v246, 22
	v_readlane_b32 s10, v246, 24
	s_cmp_ge_i32 s14, s10
	s_cselect_b64 s[0:1], -1, 0
	v_readlane_b32 s9, v246, 23
	v_readlane_b32 s11, v246, 25
	v_writelane_b32 v246, s0, 56
	s_nop 1
	v_writelane_b32 v246, s1, 57
	s_and_b64 s[0:1], s[0:1], s[6:7]
	s_andn2_b64 vcc, exec, s[0:1]
	s_cbranch_vccnz .LBB0_705
	v_readlane_b32 s0, v246, 42
	v_readlane_b32 s1, v246, 43
	s_and_b64 s[0:1], s[0:1], exec
	s_movk_i32 s0, 0x220
	s_cselect_b32 s14, s0, 0x200
	v_readlane_b32 s15, v247, 56
	s_mov_b32 s0, s3
	s_cmp_ge_i32 s15, s14
	s_mov_b32 s55, s27
	v_mbcnt_lo_u32_b32 v0, -1, 0
	v_mbcnt_hi_u32_b32 v0, -1, v0
	s_cbranch_scc0 .LBB0_551
.LBB0_546:
	s_branch .Lconv_entry
.LBB0_550:
	s_or_b64 exec, exec, s[0:1]
	s_waitcnt lgkmcnt(0)
	v_add_u32_e32 v72, s50, v181
	ds_read_b128 v[64:67], v72
	ds_read_b128 v[68:71], v72 offset:32
	s_ashr_i32 s13, s12, 31
	s_lshl_b64 s[0:1], s[12:13], 12
	s_add_u32 s0, s4, s0
	s_waitcnt lgkmcnt(1)
	v_rcp_f32_e32 v73, v64
	v_rcp_f32_e32 v74, v65
	v_rcp_f32_e32 v75, v66
	v_rcp_f32_e32 v76, v67
	ds_read_b128 v[64:67], v72 offset:64
	s_addc_u32 s1, s5, s1
	v_lshlrev_b32_e32 v160, 1, v170
	v_mul_f32_e32 v0, v0, v73
	s_waitcnt lgkmcnt(1)
	v_rcp_f32_e32 v77, v68
	v_rcp_f32_e32 v78, v69
	v_rcp_f32_e32 v79, v70
	v_rcp_f32_e32 v80, v71
	ds_read_b128 v[68:71], v72 offset:96
	s_waitcnt lgkmcnt(1)
	v_rcp_f32_e32 v72, v64
	v_rcp_f32_e32 v81, v65
	v_rcp_f32_e32 v82, v66
	v_lshl_add_u64 v[64:65], s[0:1], 0, v[160:161]
	v_lshlrev_b32_e32 v160, 14, v171
	v_bfe_u32 v66, v0, 16, 1
	v_lshl_add_u64 v[64:65], v[64:65], 0, v[160:161]
	v_add3_u32 v0, v0, v66, s37
	global_store_short_d16_hi v[64:65], v0, off
	v_mul_f32_e32 v0, v48, v73
	v_bfe_u32 v48, v0, 16, 1
	v_add3_u32 v0, v0, v48, s37
	global_store_short_d16_hi v[64:65], v0, off offset:64
	v_mul_f32_e32 v0, v32, v73
	v_bfe_u32 v32, v0, 16, 1
	v_add3_u32 v0, v0, v32, s37
	global_store_short_d16_hi v[64:65], v0, off offset:128
	v_mul_f32_e32 v0, v16, v73
	v_bfe_u32 v16, v0, 16, 1
	v_add3_u32 v0, v0, v16, s37
	global_store_short_d16_hi v[64:65], v0, off offset:192
	v_mul_f32_e32 v0, v1, v74
	v_bfe_u32 v1, v0, 16, 1
	s_movk_i32 s0, 0x1000
	v_add3_u32 v16, v0, v1, s37
	v_add_co_u32_e32 v0, vcc, s0, v64
	v_rcp_f32_e32 v83, v67
	s_nop 0
	v_addc_co_u32_e32 v1, vcc, 0, v65, vcc
	v_add_co_u32_e32 v66, vcc, s35, v64
	s_movk_i32 s0, 0x3000
	s_nop 0
	v_addc_co_u32_e32 v67, vcc, 0, v65, vcc
	global_store_short_d16_hi v[66:67], v16, off offset:-4096
	v_mul_f32_e32 v16, v49, v74
	v_bfe_u32 v32, v16, 16, 1
	v_add3_u32 v16, v16, v32, s37
	global_store_short_d16_hi v[0:1], v16, off offset:64
	v_mul_f32_e32 v16, v33, v74
	v_bfe_u32 v32, v16, 16, 1
	v_add3_u32 v16, v16, v32, s37
	global_store_short_d16_hi v[0:1], v16, off offset:128
	v_mul_f32_e32 v16, v17, v74
	v_bfe_u32 v17, v16, 16, 1
	v_add3_u32 v16, v16, v17, s37
	global_store_short_d16_hi v[0:1], v16, off offset:192
	v_mul_f32_e32 v0, v2, v75
	v_bfe_u32 v1, v0, 16, 1
	v_add3_u32 v0, v0, v1, s37
	global_store_short_d16_hi v[66:67], v0, off
	v_mul_f32_e32 v0, v50, v75
	v_bfe_u32 v1, v0, 16, 1
	v_add3_u32 v0, v0, v1, s37
	global_store_short_d16_hi v[66:67], v0, off offset:64
	v_mul_f32_e32 v0, v34, v75
	v_bfe_u32 v1, v0, 16, 1
	v_add3_u32 v0, v0, v1, s37
	global_store_short_d16_hi v[66:67], v0, off offset:128
	v_mul_f32_e32 v0, v18, v75
	v_bfe_u32 v1, v0, 16, 1
	v_add3_u32 v0, v0, v1, s37
	global_store_short_d16_hi v[66:67], v0, off offset:192
	v_mul_f32_e32 v0, v3, v76
	v_bfe_u32 v1, v0, 16, 1
	v_add3_u32 v2, v0, v1, s37
	v_add_co_u32_e32 v0, vcc, s0, v64
	s_mov_b32 s0, 0x8000
	s_nop 0
	v_addc_co_u32_e32 v1, vcc, 0, v65, vcc
	global_store_short_d16_hi v[0:1], v2, off
	v_mul_f32_e32 v2, v51, v76
	v_bfe_u32 v3, v2, 16, 1
	v_add3_u32 v2, v2, v3, s37
	global_store_short_d16_hi v[0:1], v2, off offset:64
	v_mul_f32_e32 v2, v35, v76
	v_bfe_u32 v3, v2, 16, 1
	v_add3_u32 v2, v2, v3, s37
	global_store_short_d16_hi v[0:1], v2, off offset:128
	v_mul_f32_e32 v2, v19, v76
	v_bfe_u32 v3, v2, 16, 1
	v_add3_u32 v2, v2, v3, s37
	global_store_short_d16_hi v[0:1], v2, off offset:192
	v_mul_f32_e32 v0, v4, v77
	v_bfe_u32 v1, v0, 16, 1
	v_add3_u32 v4, v0, v1, s37
	v_add_co_u32_e32 v0, vcc, s0, v64
	s_mov_b32 s0, 0x9000
	s_nop 0
	v_addc_co_u32_e32 v1, vcc, 0, v65, vcc
	v_add_co_u32_e32 v2, vcc, s0, v64
	s_mov_b32 s0, 0xa000
	s_nop 0
	v_addc_co_u32_e32 v3, vcc, 0, v65, vcc
	global_store_short_d16_hi v[2:3], v4, off offset:-4096
	v_mul_f32_e32 v4, v52, v77
	v_bfe_u32 v16, v4, 16, 1
	v_add3_u32 v4, v4, v16, s37
	global_store_short_d16_hi v[0:1], v4, off offset:64
	v_mul_f32_e32 v4, v36, v77
	v_bfe_u32 v16, v4, 16, 1
	v_add3_u32 v4, v4, v16, s37
	global_store_short_d16_hi v[0:1], v4, off offset:128
	v_mul_f32_e32 v4, v20, v77
	v_bfe_u32 v16, v4, 16, 1
	v_add3_u32 v4, v4, v16, s37
	global_store_short_d16_hi v[0:1], v4, off offset:192
	v_mul_f32_e32 v0, v5, v78
	v_bfe_u32 v1, v0, 16, 1
	v_add3_u32 v0, v0, v1, s37
	global_store_short_d16_hi v[2:3], v0, off
	v_mul_f32_e32 v0, v53, v78
	v_bfe_u32 v1, v0, 16, 1
	v_add3_u32 v0, v0, v1, s37
	global_store_short_d16_hi v[2:3], v0, off offset:64
	v_mul_f32_e32 v0, v37, v78
	v_bfe_u32 v1, v0, 16, 1
	v_add3_u32 v0, v0, v1, s37
	global_store_short_d16_hi v[2:3], v0, off offset:128
	v_mul_f32_e32 v0, v21, v78
	v_bfe_u32 v1, v0, 16, 1
	v_add3_u32 v0, v0, v1, s37
	global_store_short_d16_hi v[2:3], v0, off offset:192
	v_mul_f32_e32 v0, v6, v79
	v_bfe_u32 v1, v0, 16, 1
	v_add3_u32 v4, v0, v1, s37
	v_add_co_u32_e32 v0, vcc, s0, v64
	s_mov_b32 s0, 0xb000
	s_nop 0
	v_addc_co_u32_e32 v1, vcc, 0, v65, vcc
	v_add_co_u32_e32 v2, vcc, s0, v64
	s_mov_b32 s0, 0x10000
	s_nop 0
	v_addc_co_u32_e32 v3, vcc, 0, v65, vcc
	global_store_short_d16_hi v[2:3], v4, off offset:-4096
	v_mul_f32_e32 v4, v54, v79
	v_bfe_u32 v5, v4, 16, 1
	v_add3_u32 v4, v4, v5, s37
	global_store_short_d16_hi v[0:1], v4, off offset:64
	v_mul_f32_e32 v4, v38, v79
	v_bfe_u32 v5, v4, 16, 1
	v_add3_u32 v4, v4, v5, s37
	global_store_short_d16_hi v[0:1], v4, off offset:128
	v_mul_f32_e32 v4, v22, v79
	v_bfe_u32 v5, v4, 16, 1
	v_add3_u32 v4, v4, v5, s37
	global_store_short_d16_hi v[0:1], v4, off offset:192
	v_mul_f32_e32 v0, v7, v80
	v_bfe_u32 v1, v0, 16, 1
	v_add3_u32 v0, v0, v1, s37
	global_store_short_d16_hi v[2:3], v0, off
	v_mul_f32_e32 v0, v55, v80
	v_bfe_u32 v1, v0, 16, 1
	v_add3_u32 v0, v0, v1, s37
	global_store_short_d16_hi v[2:3], v0, off offset:64
	v_mul_f32_e32 v0, v39, v80
	v_bfe_u32 v1, v0, 16, 1
	v_add3_u32 v0, v0, v1, s37
	global_store_short_d16_hi v[2:3], v0, off offset:128
	v_mul_f32_e32 v0, v23, v80
	v_bfe_u32 v1, v0, 16, 1
	v_add3_u32 v0, v0, v1, s37
	global_store_short_d16_hi v[2:3], v0, off offset:192
	v_mul_f32_e32 v0, v8, v72
	v_bfe_u32 v1, v0, 16, 1
	v_add3_u32 v4, v0, v1, s37
	v_add_co_u32_e32 v0, vcc, s0, v64
	s_mov_b32 s0, 0x11000
	s_nop 0
	v_addc_co_u32_e32 v1, vcc, 0, v65, vcc
	v_add_co_u32_e32 v2, vcc, s0, v64
	s_mov_b32 s0, 0x12000
	s_nop 0
	v_addc_co_u32_e32 v3, vcc, 0, v65, vcc
	global_store_short_d16_hi v[2:3], v4, off offset:-4096
	v_mul_f32_e32 v4, v56, v72
	v_bfe_u32 v5, v4, 16, 1
	v_add3_u32 v4, v4, v5, s37
	global_store_short_d16_hi v[0:1], v4, off offset:64
	v_mul_f32_e32 v4, v40, v72
	v_bfe_u32 v5, v4, 16, 1
	v_add3_u32 v4, v4, v5, s37
	global_store_short_d16_hi v[0:1], v4, off offset:128
	v_mul_f32_e32 v4, v24, v72
	v_bfe_u32 v5, v4, 16, 1
	v_add3_u32 v4, v4, v5, s37
	global_store_short_d16_hi v[0:1], v4, off offset:192
	v_mul_f32_e32 v0, v9, v81
	v_bfe_u32 v1, v0, 16, 1
	v_add3_u32 v0, v0, v1, s37
	global_store_short_d16_hi v[2:3], v0, off
	v_mul_f32_e32 v0, v57, v81
	v_bfe_u32 v1, v0, 16, 1
	v_add3_u32 v0, v0, v1, s37
	global_store_short_d16_hi v[2:3], v0, off offset:64
	v_mul_f32_e32 v0, v41, v81
	v_bfe_u32 v1, v0, 16, 1
	v_add3_u32 v0, v0, v1, s37
	global_store_short_d16_hi v[2:3], v0, off offset:128
	v_mul_f32_e32 v0, v25, v81
	v_bfe_u32 v1, v0, 16, 1
	v_add3_u32 v0, v0, v1, s37
	global_store_short_d16_hi v[2:3], v0, off offset:192
	v_mul_f32_e32 v0, v10, v82
	v_bfe_u32 v1, v0, 16, 1
	v_add3_u32 v4, v0, v1, s37
	v_add_co_u32_e32 v0, vcc, s0, v64
	s_mov_b32 s0, 0x13000
	s_nop 0
	v_addc_co_u32_e32 v1, vcc, 0, v65, vcc
	v_add_co_u32_e32 v2, vcc, s0, v64
	s_waitcnt lgkmcnt(0)
	v_rcp_f32_e32 v68, v68
	v_addc_co_u32_e32 v3, vcc, 0, v65, vcc
	global_store_short_d16_hi v[2:3], v4, off offset:-4096
	v_mul_f32_e32 v4, v58, v82
	v_bfe_u32 v5, v4, 16, 1
	v_add3_u32 v4, v4, v5, s37
	global_store_short_d16_hi v[0:1], v4, off offset:64
	v_mul_f32_e32 v4, v42, v82
	v_bfe_u32 v5, v4, 16, 1
	v_add3_u32 v4, v4, v5, s37
	global_store_short_d16_hi v[0:1], v4, off offset:128
	v_mul_f32_e32 v4, v26, v82
	v_bfe_u32 v5, v4, 16, 1
	v_add3_u32 v4, v4, v5, s37
	global_store_short_d16_hi v[0:1], v4, off offset:192
	v_mul_f32_e32 v0, v11, v83
	v_bfe_u32 v1, v0, 16, 1
	v_add3_u32 v0, v0, v1, s37
	global_store_short_d16_hi v[2:3], v0, off
	v_mul_f32_e32 v0, v59, v83
	v_bfe_u32 v1, v0, 16, 1
	v_add3_u32 v0, v0, v1, s37
	global_store_short_d16_hi v[2:3], v0, off offset:64
	v_mul_f32_e32 v0, v43, v83
	v_bfe_u32 v1, v0, 16, 1
	v_add3_u32 v0, v0, v1, s37
	global_store_short_d16_hi v[2:3], v0, off offset:128
	v_mul_f32_e32 v0, v27, v83
	v_bfe_u32 v1, v0, 16, 1
	v_add3_u32 v0, v0, v1, s37
	global_store_short_d16_hi v[2:3], v0, off offset:192
	v_mul_f32_e32 v0, v12, v68
	v_bfe_u32 v1, v0, 16, 1
	s_mov_b32 s0, 0x18000
	v_add3_u32 v4, v0, v1, s37
	v_add_co_u32_e32 v0, vcc, s0, v64
	s_mov_b32 s0, 0x19000
	s_nop 0
	v_addc_co_u32_e32 v1, vcc, 0, v65, vcc
	v_add_co_u32_e32 v2, vcc, s0, v64
	v_rcp_f32_e32 v69, v69
	s_nop 0
	v_addc_co_u32_e32 v3, vcc, 0, v65, vcc
	global_store_short_d16_hi v[2:3], v4, off offset:-4096
	v_mul_f32_e32 v4, v60, v68
	v_bfe_u32 v5, v4, 16, 1
	v_add3_u32 v4, v4, v5, s37
	global_store_short_d16_hi v[0:1], v4, off offset:64
	v_mul_f32_e32 v4, v44, v68
	v_bfe_u32 v5, v4, 16, 1
	v_add3_u32 v4, v4, v5, s37
	global_store_short_d16_hi v[0:1], v4, off offset:128
	v_mul_f32_e32 v4, v28, v68
	v_bfe_u32 v5, v4, 16, 1
	v_add3_u32 v4, v4, v5, s37
	global_store_short_d16_hi v[0:1], v4, off offset:192
	v_mul_f32_e32 v0, v13, v69
	v_bfe_u32 v1, v0, 16, 1
	v_add3_u32 v0, v0, v1, s37
	global_store_short_d16_hi v[2:3], v0, off
	v_mul_f32_e32 v0, v61, v69
	v_bfe_u32 v1, v0, 16, 1
	v_add3_u32 v0, v0, v1, s37
	global_store_short_d16_hi v[2:3], v0, off offset:64
	v_mul_f32_e32 v0, v45, v69
	v_bfe_u32 v1, v0, 16, 1
	v_rcp_f32_e32 v70, v70
	v_add3_u32 v0, v0, v1, s37
	global_store_short_d16_hi v[2:3], v0, off offset:128
	v_mul_f32_e32 v0, v29, v69
	v_bfe_u32 v1, v0, 16, 1
	v_add3_u32 v0, v0, v1, s37
	global_store_short_d16_hi v[2:3], v0, off offset:192
	v_mul_f32_e32 v0, v14, v70
	v_bfe_u32 v1, v0, 16, 1
	s_mov_b32 s0, 0x1a000
	v_add3_u32 v4, v0, v1, s37
	v_add_co_u32_e32 v0, vcc, s0, v64
	s_mov_b32 s0, 0x1b000
	s_nop 0
	v_addc_co_u32_e32 v1, vcc, 0, v65, vcc
	v_add_co_u32_e32 v2, vcc, s0, v64
	v_rcp_f32_e32 v71, v71
	s_nop 0
	v_addc_co_u32_e32 v3, vcc, 0, v65, vcc
	global_store_short_d16_hi v[2:3], v4, off offset:-4096
	v_mul_f32_e32 v4, v62, v70
	v_bfe_u32 v5, v4, 16, 1
	v_add3_u32 v4, v4, v5, s37
	global_store_short_d16_hi v[0:1], v4, off offset:64
	v_mul_f32_e32 v4, v46, v70
	v_bfe_u32 v5, v4, 16, 1
	v_add3_u32 v4, v4, v5, s37
	global_store_short_d16_hi v[0:1], v4, off offset:128
	v_mul_f32_e32 v4, v30, v70
	v_bfe_u32 v5, v4, 16, 1
	v_add3_u32 v4, v4, v5, s37
	global_store_short_d16_hi v[0:1], v4, off offset:192
	v_mul_f32_e32 v0, v15, v71
	v_bfe_u32 v1, v0, 16, 1
	v_add3_u32 v0, v0, v1, s37
	global_store_short_d16_hi v[2:3], v0, off
	v_mul_f32_e32 v0, v63, v71
	v_bfe_u32 v1, v0, 16, 1
	v_add3_u32 v0, v0, v1, s37
	global_store_short_d16_hi v[2:3], v0, off offset:64
	v_mul_f32_e32 v0, v47, v71
	v_bfe_u32 v1, v0, 16, 1
	v_add3_u32 v0, v0, v1, s37
	global_store_short_d16_hi v[2:3], v0, off offset:128
	v_mul_f32_e32 v0, v31, v71
	v_bfe_u32 v1, v0, 16, 1
	v_add3_u32 v0, v0, v1, s37
	global_store_short_d16_hi v[2:3], v0, off offset:192
	s_waitcnt lgkmcnt(0)
	s_barrier
	s_add_i32 s15, s15, s34
	s_cmp_lt_i32 s15, s14
	s_cbranch_scc0 .LBB0_729

.LBB0_561:
	s_waitcnt lgkmcnt(0)
	s_barrier
	v_add_f32_e32 v212, 0, v150
	v_add_f32_e32 v212, v152, v212
	v_add_f32_e32 v212, v145, v212
	v_add_f32_e32 v212, v151, v212
	v_add_f32_e32 v212, v146, v212
	v_add_f32_e32 v212, v149, v212
	v_add_f32_e32 v212, v147, v212
	v_add_f32_e32 v212, v148, v212
	v_add_f32_e32 v212, v93, v212
	v_add_f32_e32 v212, v95, v212
	v_add_f32_e32 v212, v91, v212
	v_add_f32_e32 v212, v94, v212
	v_add_f32_e32 v212, v89, v212
	v_add_f32_e32 v212, v92, v212
	v_add_f32_e32 v212, v88, v212
	v_add_f32_e32 v212, v90, v212
	v_cvt_pk_bf16_f32 v144, v150, v152
	v_cvt_pk_bf16_f32 v145, v145, v151
	v_cvt_pk_bf16_f32 v146, v146, v149
	v_cvt_pk_bf16_f32 v147, v147, v148
	v_cvt_pk_bf16_f32 v148, v93, v95
	v_cvt_pk_bf16_f32 v149, v91, v94
	v_cvt_pk_bf16_f32 v150, v89, v92
	v_cvt_pk_bf16_f32 v151, v88, v90
	v_mov_b32_e32 v72, v70
	v_mov_b32_e32 v73, v71
	v_mov_b32_e32 v74, v68
	v_mov_b32_e32 v75, v69
	v_mov_b32_e32 v76, v66
	v_mov_b32_e32 v77, v67
	v_mov_b32_e32 v78, v64
	v_mov_b32_e32 v79, v65
	v_mov_b32_e32 v64, v86
	v_mov_b32_e32 v65, v87
	v_mov_b32_e32 v66, v84
	v_mov_b32_e32 v67, v85
	v_mov_b32_e32 v68, v82
	v_mov_b32_e32 v69, v83
	v_mov_b32_e32 v70, v80
	v_mov_b32_e32 v71, v81
	v_permlane32_swap_b32_e32 v144, v146
	v_permlane32_swap_b32_e32 v145, v147
	v_permlane32_swap_b32_e32 v148, v150
	v_permlane32_swap_b32_e32 v149, v151

.Lconv_entry:
	v_mbcnt_lo_u32_b32 v152, -1, 0
	v_mbcnt_hi_u32_b32 v152, -1, v152
	v_lshl_add_u32 v153, s3, 6, v152
	v_lshlrev_b32_e32 v142, 1, v153
	v_lshlrev_b32_e32 v143, 2, v153
	v_lshrrev_b32_e32 v154, 5, v153
	v_and_b32_e32 v155, 31, v153
	v_lshlrev_b32_e32 v144, 11, v154
	v_lshl_add_u32 v144, v155, 6, v144
	v_lshlrev_b32_e32 v145, 3, v154
	v_add_u32_e32 v145, 0x8000, v145
	v_mov_b32_e32 v151, 0x8000
	v_xor_b32_e32 v146, 1, v152
	v_lshlrev_b32_e32 v146, 2, v146
	v_xor_b32_e32 v147, 2, v152
	v_lshlrev_b32_e32 v147, 2, v147
	v_xor_b32_e32 v148, 4, v152
	v_lshlrev_b32_e32 v148, 2, v148
	v_xor_b32_e32 v149, 8, v152
	v_lshlrev_b32_e32 v149, 2, v149
	v_xor_b32_e32 v150, 16, v152
	v_lshlrev_b32_e32 v150, 2, v150
	s_mov_b32 s72, s55
	v_readlane_b32 s71, v246, 55
	v_readlane_b32 s84, v248, 14
	v_readlane_b32 s85, v248, 15
	v_readlane_b32 s86, v248, 16
	v_readlane_b32 s87, v248, 17
	v_readlane_b32 s90, v248, 18
	v_readlane_b32 s91, v248, 19
	v_readlane_b32 s92, v248, 20
	v_readlane_b32 s93, v248, 21
	s_nop 3
	s_lshr_b32 s71, s71, 4
	s_mov_b32 s70, s2
	s_cmp_ge_i32 s70, s71
	s_cbranch_scc1 .LBB0_705
	s_mul_i32 s80, s72, 0xf800
	s_add_u32 s84, s84, s80
	s_addc_u32 s85, s85, 0
	global_load_dword v92, v143, s[84:85]
	s_add_u32 s84, s84, 0x800
	s_addc_u32 s85, s85, 0
	global_load_dword v93, v143, s[84:85]
	s_add_u32 s84, s84, 0x800
	s_addc_u32 s85, s85, 0
	global_load_dword v94, v143, s[84:85]
	s_add_u32 s84, s84, 0x800
	s_addc_u32 s85, s85, 0
	global_load_dword v95, v143, s[84:85]
	s_add_u32 s84, s84, 0x800
	s_addc_u32 s85, s85, 0
	global_load_dword v96, v143, s[84:85]
	s_add_u32 s84, s84, 0x800
	s_addc_u32 s85, s85, 0
	global_load_dword v97, v143, s[84:85]
	s_add_u32 s84, s84, 0x800
	s_addc_u32 s85, s85, 0
	global_load_dword v98, v143, s[84:85]
	s_add_u32 s84, s84, 0x800
	s_addc_u32 s85, s85, 0
	global_load_dword v99, v143, s[84:85]
	s_add_u32 s84, s84, 0x800
	s_addc_u32 s85, s85, 0
	global_load_dword v100, v143, s[84:85]
	s_add_u32 s84, s84, 0x800
	s_addc_u32 s85, s85, 0
	global_load_dword v101, v143, s[84:85]
	s_add_u32 s84, s84, 0x800
	s_addc_u32 s85, s85, 0
	global_load_dword v102, v143, s[84:85]
	s_add_u32 s84, s84, 0x800
	s_addc_u32 s85, s85, 0
	global_load_dword v103, v143, s[84:85]
	s_add_u32 s84, s84, 0x800
	s_addc_u32 s85, s85, 0
	global_load_dword v104, v143, s[84:85]
	s_add_u32 s84, s84, 0x800
	s_addc_u32 s85, s85, 0
	global_load_dword v105, v143, s[84:85]
	s_add_u32 s84, s84, 0x800
	s_addc_u32 s85, s85, 0
	global_load_dword v106, v143, s[84:85]
	s_add_u32 s84, s84, 0x800
	s_addc_u32 s85, s85, 0
	global_load_dword v107, v143, s[84:85]
	s_add_u32 s84, s84, 0x800
	s_addc_u32 s85, s85, 0
	global_load_dword v108, v143, s[84:85]
	s_add_u32 s84, s84, 0x800
	s_addc_u32 s85, s85, 0
	global_load_dword v109, v143, s[84:85]
	s_add_u32 s84, s84, 0x800
	s_addc_u32 s85, s85, 0
	global_load_dword v110, v143, s[84:85]
	s_add_u32 s84, s84, 0x800
	s_addc_u32 s85, s85, 0
	global_load_dword v111, v143, s[84:85]
	s_add_u32 s84, s84, 0x800
	s_addc_u32 s85, s85, 0
	global_load_dword v112, v143, s[84:85]
	s_add_u32 s84, s84, 0x800
	s_addc_u32 s85, s85, 0
	global_load_dword v113, v143, s[84:85]
	s_add_u32 s84, s84, 0x800
	s_addc_u32 s85, s85, 0
	global_load_dword v114, v143, s[84:85]
	s_add_u32 s84, s84, 0x800
	s_addc_u32 s85, s85, 0
	global_load_dword v115, v143, s[84:85]
	s_add_u32 s84, s84, 0x800
	s_addc_u32 s85, s85, 0
	global_load_dword v116, v143, s[84:85]
	s_add_u32 s84, s84, 0x800
	s_addc_u32 s85, s85, 0
	global_load_dword v117, v143, s[84:85]
	s_add_u32 s84, s84, 0x800
	s_addc_u32 s85, s85, 0
	global_load_dword v118, v143, s[84:85]
	s_add_u32 s84, s84, 0x800
	s_addc_u32 s85, s85, 0
	global_load_dword v119, v143, s[84:85]
	s_add_u32 s84, s84, 0x800
	s_addc_u32 s85, s85, 0
	global_load_dword v120, v143, s[84:85]
	s_add_u32 s84, s84, 0x800
	s_addc_u32 s85, s85, 0
	global_load_dword v121, v143, s[84:85]
	s_add_u32 s84, s84, 0x800
	s_addc_u32 s85, s85, 0
	global_load_dword v122, v143, s[84:85]
	s_lshl_b32 s80, s72, 11
	s_add_u32 s86, s86, s80
	s_addc_u32 s87, s87, 0
	s_add_u32 s90, s90, s80
	s_addc_u32 s91, s91, 0
	s_add_u32 s92, s92, s80
	s_addc_u32 s93, s93, 0
	global_load_dword v123, v143, s[86:87]
	global_load_dword v124, v143, s[90:91]
	global_load_dword v125, v143, s[92:93]
	s_waitcnt vmcnt(0)
	s_lshl_b32 s73, s70, 4
	s_and_b32 s74, s73, 0xfffff000
	s_add_i32 s75, s74, 0xfff
	s_and_b32 s80, s73, 0x7fffff00
	s_add_i32 s81, s80, 0xff
	s_cmpk_lt_i32 s70, 0x400
	s_cselect_b32 s74, s74, s80
	s_cselect_b32 s75, s75, s81
	s_add_i32 s80, s73, -15
	s_max_i32 s80, s80, s74
	s_mul_i32 s80, s80, 0x1800
	s_add_u32 s82, s42, s80
	s_addc_u32 s83, s43, 0
	global_load_ushort v0, v142, s[82:83] offset:3712
	s_add_i32 s80, s73, -14
	s_max_i32 s80, s80, s74
	s_mul_i32 s80, s80, 0x1800
	s_add_u32 s82, s42, s80
	s_addc_u32 s83, s43, 0
	global_load_ushort v1, v142, s[82:83] offset:3712
	s_add_i32 s80, s73, -13
	s_max_i32 s80, s80, s74
	s_mul_i32 s80, s80, 0x1800
	s_add_u32 s82, s42, s80
	s_addc_u32 s83, s43, 0
	global_load_ushort v2, v142, s[82:83] offset:3712
	s_add_i32 s80, s73, -12
	s_max_i32 s80, s80, s74
	s_mul_i32 s80, s80, 0x1800
	s_add_u32 s82, s42, s80
	s_addc_u32 s83, s43, 0
	global_load_ushort v3, v142, s[82:83] offset:3712
	s_add_i32 s80, s73, -11
	s_max_i32 s80, s80, s74
	s_mul_i32 s80, s80, 0x1800
	s_add_u32 s82, s42, s80
	s_addc_u32 s83, s43, 0
	global_load_ushort v4, v142, s[82:83] offset:3712
	s_add_i32 s80, s73, -10
	s_max_i32 s80, s80, s74
	s_mul_i32 s80, s80, 0x1800
	s_add_u32 s82, s42, s80
	s_addc_u32 s83, s43, 0
	global_load_ushort v5, v142, s[82:83] offset:3712
	s_add_i32 s80, s73, -9
	s_max_i32 s80, s80, s74
	s_mul_i32 s80, s80, 0x1800
	s_add_u32 s82, s42, s80
	s_addc_u32 s83, s43, 0
	global_load_ushort v6, v142, s[82:83] offset:3712
	s_add_i32 s80, s73, -8
	s_max_i32 s80, s80, s74
	s_mul_i32 s80, s80, 0x1800
	s_add_u32 s82, s42, s80
	s_addc_u32 s83, s43, 0
	global_load_ushort v7, v142, s[82:83] offset:3712
	s_add_i32 s80, s73, -7
	s_max_i32 s80, s80, s74
	s_mul_i32 s80, s80, 0x1800
	s_add_u32 s82, s42, s80
	s_addc_u32 s83, s43, 0
	global_load_ushort v8, v142, s[82:83] offset:3712
	s_add_i32 s80, s73, -6
	s_max_i32 s80, s80, s74
	s_mul_i32 s80, s80, 0x1800
	s_add_u32 s82, s42, s80
	s_addc_u32 s83, s43, 0
	global_load_ushort v9, v142, s[82:83] offset:3712
	s_add_i32 s80, s73, -5
	s_max_i32 s80, s80, s74
	s_mul_i32 s80, s80, 0x1800
	s_add_u32 s82, s42, s80
	s_addc_u32 s83, s43, 0
	global_load_ushort v10, v142, s[82:83] offset:3712
	s_add_i32 s80, s73, -4
	s_max_i32 s80, s80, s74
	s_mul_i32 s80, s80, 0x1800
	s_add_u32 s82, s42, s80
	s_addc_u32 s83, s43, 0
	global_load_ushort v11, v142, s[82:83] offset:3712
	s_add_i32 s80, s73, -3
	s_max_i32 s80, s80, s74
	s_mul_i32 s80, s80, 0x1800
	s_add_u32 s82, s42, s80
	s_addc_u32 s83, s43, 0
	global_load_ushort v12, v142, s[82:83] offset:3712
	s_add_i32 s80, s73, -2
	s_max_i32 s80, s80, s74
	s_mul_i32 s80, s80, 0x1800
	s_add_u32 s82, s42, s80
	s_addc_u32 s83, s43, 0
	global_load_ushort v13, v142, s[82:83] offset:3712
	s_add_i32 s80, s73, -1
	s_max_i32 s80, s80, s74
	s_mul_i32 s80, s80, 0x1800
	s_add_u32 s82, s42, s80
	s_addc_u32 s83, s43, 0
	global_load_ushort v14, v142, s[82:83] offset:3712
	s_add_i32 s80, s73, 0
	s_mul_i32 s80, s80, 0x1800
	s_add_u32 s82, s42, s80
	s_addc_u32 s83, s43, 0
	global_load_ushort v15, v142, s[82:83] offset:3712
	s_add_i32 s80, s73, 1
	s_mul_i32 s80, s80, 0x1800
	s_add_u32 s82, s42, s80
	s_addc_u32 s83, s43, 0
	global_load_ushort v16, v142, s[82:83] offset:3712
	s_add_i32 s80, s73, 2
	s_mul_i32 s80, s80, 0x1800
	s_add_u32 s82, s42, s80
	s_addc_u32 s83, s43, 0
	global_load_ushort v17, v142, s[82:83] offset:3712
	s_add_i32 s80, s73, 3
	s_mul_i32 s80, s80, 0x1800
	s_add_u32 s82, s42, s80
	s_addc_u32 s83, s43, 0
	global_load_ushort v18, v142, s[82:83] offset:3712
	s_add_i32 s80, s73, 4
	s_mul_i32 s80, s80, 0x1800
	s_add_u32 s82, s42, s80
	s_addc_u32 s83, s43, 0
	global_load_ushort v19, v142, s[82:83] offset:3712
	s_add_i32 s80, s73, 5
	s_mul_i32 s80, s80, 0x1800
	s_add_u32 s82, s42, s80
	s_addc_u32 s83, s43, 0
	global_load_ushort v20, v142, s[82:83] offset:3712
	s_add_i32 s80, s73, 6
	s_mul_i32 s80, s80, 0x1800
	s_add_u32 s82, s42, s80
	s_addc_u32 s83, s43, 0
	global_load_ushort v21, v142, s[82:83] offset:3712
	s_add_i32 s80, s73, 7
	s_mul_i32 s80, s80, 0x1800
	s_add_u32 s82, s42, s80
	s_addc_u32 s83, s43, 0
	global_load_ushort v22, v142, s[82:83] offset:3712
	s_add_i32 s80, s73, 8
	s_mul_i32 s80, s80, 0x1800
	s_add_u32 s82, s42, s80
	s_addc_u32 s83, s43, 0
	global_load_ushort v23, v142, s[82:83] offset:3712
	s_add_i32 s80, s73, 9
	s_mul_i32 s80, s80, 0x1800
	s_add_u32 s82, s42, s80
	s_addc_u32 s83, s43, 0
	global_load_ushort v24, v142, s[82:83] offset:3712
	s_add_i32 s80, s73, 10
	s_mul_i32 s80, s80, 0x1800
	s_add_u32 s82, s42, s80
	s_addc_u32 s83, s43, 0
	global_load_ushort v25, v142, s[82:83] offset:3712
	s_add_i32 s80, s73, 11
	s_mul_i32 s80, s80, 0x1800
	s_add_u32 s82, s42, s80
	s_addc_u32 s83, s43, 0
	global_load_ushort v26, v142, s[82:83] offset:3712
	s_add_i32 s80, s73, 12
	s_mul_i32 s80, s80, 0x1800
	s_add_u32 s82, s42, s80
	s_addc_u32 s83, s43, 0
	global_load_ushort v27, v142, s[82:83] offset:3712
	s_add_i32 s80, s73, 13
	s_mul_i32 s80, s80, 0x1800
	s_add_u32 s82, s42, s80
	s_addc_u32 s83, s43, 0
	global_load_ushort v28, v142, s[82:83] offset:3712
	s_add_i32 s80, s73, 14
	s_mul_i32 s80, s80, 0x1800
	s_add_u32 s82, s42, s80
	s_addc_u32 s83, s43, 0
	global_load_ushort v29, v142, s[82:83] offset:3712
	s_add_i32 s80, s73, 15
	s_mul_i32 s80, s80, 0x1800
	s_add_u32 s82, s42, s80
	s_addc_u32 s83, s43, 0
	global_load_ushort v30, v142, s[82:83] offset:3712
	s_add_i32 s80, s73, 16
	s_min_i32 s80, s80, s75
	s_mul_i32 s80, s80, 0x1800
	s_add_u32 s82, s42, s80
	s_addc_u32 s83, s43, 0
	global_load_ushort v31, v142, s[82:83] offset:3712
	s_add_i32 s80, s73, 17
	s_min_i32 s80, s80, s75
	s_mul_i32 s80, s80, 0x1800
	s_add_u32 s82, s42, s80
	s_addc_u32 s83, s43, 0
	global_load_ushort v32, v142, s[82:83] offset:3712
	s_add_i32 s80, s73, 18
	s_min_i32 s80, s80, s75
	s_mul_i32 s80, s80, 0x1800
	s_add_u32 s82, s42, s80
	s_addc_u32 s83, s43, 0
	global_load_ushort v33, v142, s[82:83] offset:3712
	s_add_i32 s80, s73, 19
	s_min_i32 s80, s80, s75
	s_mul_i32 s80, s80, 0x1800
	s_add_u32 s82, s42, s80
	s_addc_u32 s83, s43, 0
	global_load_ushort v34, v142, s[82:83] offset:3712
	s_add_i32 s80, s73, 20
	s_min_i32 s80, s80, s75
	s_mul_i32 s80, s80, 0x1800
	s_add_u32 s82, s42, s80
	s_addc_u32 s83, s43, 0
	global_load_ushort v35, v142, s[82:83] offset:3712
	s_add_i32 s80, s73, 21
	s_min_i32 s80, s80, s75
	s_mul_i32 s80, s80, 0x1800
	s_add_u32 s82, s42, s80
	s_addc_u32 s83, s43, 0
	global_load_ushort v36, v142, s[82:83] offset:3712
	s_add_i32 s80, s73, 22
	s_min_i32 s80, s80, s75
	s_mul_i32 s80, s80, 0x1800
	s_add_u32 s82, s42, s80
	s_addc_u32 s83, s43, 0
	global_load_ushort v37, v142, s[82:83] offset:3712
	s_add_i32 s80, s73, 23
	s_min_i32 s80, s80, s75
	s_mul_i32 s80, s80, 0x1800
	s_add_u32 s82, s42, s80
	s_addc_u32 s83, s43, 0
	global_load_ushort v38, v142, s[82:83] offset:3712
	s_add_i32 s80, s73, 24
	s_min_i32 s80, s80, s75
	s_mul_i32 s80, s80, 0x1800
	s_add_u32 s82, s42, s80
	s_addc_u32 s83, s43, 0
	global_load_ushort v39, v142, s[82:83] offset:3712
	s_add_i32 s80, s73, 25
	s_min_i32 s80, s80, s75
	s_mul_i32 s80, s80, 0x1800
	s_add_u32 s82, s42, s80
	s_addc_u32 s83, s43, 0
	global_load_ushort v40, v142, s[82:83] offset:3712
	s_add_i32 s80, s73, 26
	s_min_i32 s80, s80, s75
	s_mul_i32 s80, s80, 0x1800
	s_add_u32 s82, s42, s80
	s_addc_u32 s83, s43, 0
	global_load_ushort v41, v142, s[82:83] offset:3712
	s_add_i32 s80, s73, 27
	s_min_i32 s80, s80, s75
	s_mul_i32 s80, s80, 0x1800
	s_add_u32 s82, s42, s80
	s_addc_u32 s83, s43, 0
	global_load_ushort v42, v142, s[82:83] offset:3712
	s_add_i32 s80, s73, 28
	s_min_i32 s80, s80, s75
	s_mul_i32 s80, s80, 0x1800
	s_add_u32 s82, s42, s80
	s_addc_u32 s83, s43, 0
	global_load_ushort v43, v142, s[82:83] offset:3712
	s_add_i32 s80, s73, 29
	s_min_i32 s80, s80, s75
	s_mul_i32 s80, s80, 0x1800
	s_add_u32 s82, s42, s80
	s_addc_u32 s83, s43, 0
	global_load_ushort v44, v142, s[82:83] offset:3712
	s_add_i32 s80, s73, 30
	s_min_i32 s80, s80, s75
	s_mul_i32 s80, s80, 0x1800
	s_add_u32 s82, s42, s80
	s_addc_u32 s83, s43, 0
	global_load_ushort v45, v142, s[82:83] offset:3712
	s_waitcnt vmcnt(0)
.Lconv_loop:
	s_waitcnt vmcnt(16)
	s_lshl_b32 s73, s70, 4
	s_and_b32 s74, s73, 0xfffff000
	s_add_i32 s75, s74, 0xfff
	s_and_b32 s80, s73, 0x7fffff00
	s_add_i32 s81, s80, 0xff
	s_cmpk_lt_i32 s70, 0x400
	s_cselect_b32 s74, s74, s80
	s_cselect_b32 s75, s75, s81
	s_cmp_eq_u32 s73, s74
	s_cselect_b64 s[76:77], -1, 0
	s_add_i32 s80, s73, 15
	s_cmp_eq_u32 s80, s75
	s_cselect_b64 s[94:95], -1, 0
	v_lshlrev_b32_e32 v46, 16, v0
	v_lshlrev_b32_e32 v47, 16, v1
	v_lshlrev_b32_e32 v48, 16, v2
	v_lshlrev_b32_e32 v49, 16, v3
	v_lshlrev_b32_e32 v50, 16, v4
	v_lshlrev_b32_e32 v51, 16, v5
	v_lshlrev_b32_e32 v52, 16, v6
	v_lshlrev_b32_e32 v53, 16, v7
	v_lshlrev_b32_e32 v54, 16, v8
	v_lshlrev_b32_e32 v55, 16, v9
	v_lshlrev_b32_e32 v56, 16, v10
	v_lshlrev_b32_e32 v57, 16, v11
	v_lshlrev_b32_e32 v58, 16, v12
	v_lshlrev_b32_e32 v59, 16, v13
	v_lshlrev_b32_e32 v60, 16, v14
	v_lshlrev_b32_e32 v61, 16, v15
	v_lshlrev_b32_e32 v62, 16, v16
	v_lshlrev_b32_e32 v63, 16, v17
	v_lshlrev_b32_e32 v64, 16, v18
	v_lshlrev_b32_e32 v65, 16, v19
	v_lshlrev_b32_e32 v66, 16, v20
	v_lshlrev_b32_e32 v67, 16, v21
	v_lshlrev_b32_e32 v68, 16, v22
	v_lshlrev_b32_e32 v69, 16, v23
	v_lshlrev_b32_e32 v70, 16, v24
	v_lshlrev_b32_e32 v71, 16, v25
	v_lshlrev_b32_e32 v72, 16, v26
	v_lshlrev_b32_e32 v73, 16, v27
	v_lshlrev_b32_e32 v74, 16, v28
	v_lshlrev_b32_e32 v75, 16, v29
	v_lshlrev_b32_e32 v76, 16, v30
	v_lshlrev_b32_e32 v77, 16, v31
	v_lshlrev_b32_e32 v78, 16, v32
	v_lshlrev_b32_e32 v79, 16, v33
	v_lshlrev_b32_e32 v80, 16, v34
	v_lshlrev_b32_e32 v81, 16, v35
	v_lshlrev_b32_e32 v82, 16, v36
	v_lshlrev_b32_e32 v83, 16, v37
	v_lshlrev_b32_e32 v84, 16, v38
	v_lshlrev_b32_e32 v85, 16, v39
	v_lshlrev_b32_e32 v86, 16, v40
	v_lshlrev_b32_e32 v87, 16, v41
	v_lshlrev_b32_e32 v88, 16, v42
	v_lshlrev_b32_e32 v89, 16, v43
	v_lshlrev_b32_e32 v90, 16, v44
	v_lshlrev_b32_e32 v91, 16, v45
	v_cndmask_b32_e64 v46, v46, 0, s[76:77]
	v_cndmask_b32_e64 v47, v47, 0, s[76:77]
	v_cndmask_b32_e64 v48, v48, 0, s[76:77]
	v_cndmask_b32_e64 v49, v49, 0, s[76:77]
	v_cndmask_b32_e64 v50, v50, 0, s[76:77]
	v_cndmask_b32_e64 v51, v51, 0, s[76:77]
	v_cndmask_b32_e64 v52, v52, 0, s[76:77]
	v_cndmask_b32_e64 v53, v53, 0, s[76:77]
	v_cndmask_b32_e64 v54, v54, 0, s[76:77]
	v_cndmask_b32_e64 v55, v55, 0, s[76:77]
	v_cndmask_b32_e64 v56, v56, 0, s[76:77]
	v_cndmask_b32_e64 v57, v57, 0, s[76:77]
	v_cndmask_b32_e64 v58, v58, 0, s[76:77]
	v_cndmask_b32_e64 v59, v59, 0, s[76:77]
	v_cndmask_b32_e64 v60, v60, 0, s[76:77]
	v_cndmask_b32_e64 v77, v77, 0, s[94:95]
	v_cndmask_b32_e64 v78, v78, 0, s[94:95]
	v_cndmask_b32_e64 v79, v79, 0, s[94:95]
	v_cndmask_b32_e64 v80, v80, 0, s[94:95]
	v_cndmask_b32_e64 v81, v81, 0, s[94:95]
	v_cndmask_b32_e64 v82, v82, 0, s[94:95]
	v_cndmask_b32_e64 v83, v83, 0, s[94:95]
	v_cndmask_b32_e64 v84, v84, 0, s[94:95]
	v_cndmask_b32_e64 v85, v85, 0, s[94:95]
	v_cndmask_b32_e64 v86, v86, 0, s[94:95]
	v_cndmask_b32_e64 v87, v87, 0, s[94:95]
	v_cndmask_b32_e64 v88, v88, 0, s[94:95]
	v_cndmask_b32_e64 v89, v89, 0, s[94:95]
	v_cndmask_b32_e64 v90, v90, 0, s[94:95]
	v_cndmask_b32_e64 v91, v91, 0, s[94:95]
	s_add_i32 s96, s70, s34
	s_cmp_ge_i32 s96, s71
	s_cselect_b32 s96, s70, s96
	s_lshl_b32 s73, s96, 4
	s_and_b32 s74, s73, 0xfffff000
	s_add_i32 s75, s74, 0xfff
	s_and_b32 s80, s73, 0x7fffff00
	s_add_i32 s81, s80, 0xff
	s_cmpk_lt_i32 s96, 0x400
	s_cselect_b32 s74, s74, s80
	s_cselect_b32 s75, s75, s81
	s_add_i32 s80, s73, -15
	s_max_i32 s80, s80, s74
	s_mul_i32 s80, s80, 0x1800
	s_add_u32 s82, s42, s80
	s_addc_u32 s83, s43, 0
	global_load_ushort v0, v142, s[82:83] offset:3712
	s_add_i32 s80, s73, -14
	s_max_i32 s80, s80, s74
	s_mul_i32 s80, s80, 0x1800
	s_add_u32 s82, s42, s80
	s_addc_u32 s83, s43, 0
	global_load_ushort v1, v142, s[82:83] offset:3712
	s_add_i32 s80, s73, -13
	s_max_i32 s80, s80, s74
	s_mul_i32 s80, s80, 0x1800
	s_add_u32 s82, s42, s80
	s_addc_u32 s83, s43, 0
	global_load_ushort v2, v142, s[82:83] offset:3712
	s_add_i32 s80, s73, -12
	s_max_i32 s80, s80, s74
	s_mul_i32 s80, s80, 0x1800
	s_add_u32 s82, s42, s80
	s_addc_u32 s83, s43, 0
	global_load_ushort v3, v142, s[82:83] offset:3712
	s_add_i32 s80, s73, -11
	s_max_i32 s80, s80, s74
	s_mul_i32 s80, s80, 0x1800
	s_add_u32 s82, s42, s80
	s_addc_u32 s83, s43, 0
	global_load_ushort v4, v142, s[82:83] offset:3712
	s_add_i32 s80, s73, -10
	s_max_i32 s80, s80, s74
	s_mul_i32 s80, s80, 0x1800
	s_add_u32 s82, s42, s80
	s_addc_u32 s83, s43, 0
	global_load_ushort v5, v142, s[82:83] offset:3712
	s_add_i32 s80, s73, -9
	s_max_i32 s80, s80, s74
	s_mul_i32 s80, s80, 0x1800
	s_add_u32 s82, s42, s80
	s_addc_u32 s83, s43, 0
	global_load_ushort v6, v142, s[82:83] offset:3712
	s_add_i32 s80, s73, -8
	s_max_i32 s80, s80, s74
	s_mul_i32 s80, s80, 0x1800
	s_add_u32 s82, s42, s80
	s_addc_u32 s83, s43, 0
	global_load_ushort v7, v142, s[82:83] offset:3712
	s_add_i32 s80, s73, -7
	s_max_i32 s80, s80, s74
	s_mul_i32 s80, s80, 0x1800
	s_add_u32 s82, s42, s80
	s_addc_u32 s83, s43, 0
	global_load_ushort v8, v142, s[82:83] offset:3712
	s_add_i32 s80, s73, -6
	s_max_i32 s80, s80, s74
	s_mul_i32 s80, s80, 0x1800
	s_add_u32 s82, s42, s80
	s_addc_u32 s83, s43, 0
	global_load_ushort v9, v142, s[82:83] offset:3712
	s_add_i32 s80, s73, -5
	s_max_i32 s80, s80, s74
	s_mul_i32 s80, s80, 0x1800
	s_add_u32 s82, s42, s80
	s_addc_u32 s83, s43, 0
	global_load_ushort v10, v142, s[82:83] offset:3712
	s_add_i32 s80, s73, -4
	s_max_i32 s80, s80, s74
	s_mul_i32 s80, s80, 0x1800
	s_add_u32 s82, s42, s80
	s_addc_u32 s83, s43, 0
	global_load_ushort v11, v142, s[82:83] offset:3712
	s_add_i32 s80, s73, -3
	s_max_i32 s80, s80, s74
	s_mul_i32 s80, s80, 0x1800
	s_add_u32 s82, s42, s80
	s_addc_u32 s83, s43, 0
	global_load_ushort v12, v142, s[82:83] offset:3712
	s_add_i32 s80, s73, -2
	s_max_i32 s80, s80, s74
	s_mul_i32 s80, s80, 0x1800
	s_add_u32 s82, s42, s80
	s_addc_u32 s83, s43, 0
	global_load_ushort v13, v142, s[82:83] offset:3712
	s_add_i32 s80, s73, -1
	s_max_i32 s80, s80, s74
	s_mul_i32 s80, s80, 0x1800
	s_add_u32 s82, s42, s80
	s_addc_u32 s83, s43, 0
	global_load_ushort v14, v142, s[82:83] offset:3712
	s_add_i32 s80, s73, 0
	s_mul_i32 s80, s80, 0x1800
	s_add_u32 s82, s42, s80
	s_addc_u32 s83, s43, 0
	global_load_ushort v15, v142, s[82:83] offset:3712
	s_add_i32 s80, s73, 1
	s_mul_i32 s80, s80, 0x1800
	s_add_u32 s82, s42, s80
	s_addc_u32 s83, s43, 0
	global_load_ushort v16, v142, s[82:83] offset:3712
	s_add_i32 s80, s73, 2
	s_mul_i32 s80, s80, 0x1800
	s_add_u32 s82, s42, s80
	s_addc_u32 s83, s43, 0
	global_load_ushort v17, v142, s[82:83] offset:3712
	s_add_i32 s80, s73, 3
	s_mul_i32 s80, s80, 0x1800
	s_add_u32 s82, s42, s80
	s_addc_u32 s83, s43, 0
	global_load_ushort v18, v142, s[82:83] offset:3712
	s_add_i32 s80, s73, 4
	s_mul_i32 s80, s80, 0x1800
	s_add_u32 s82, s42, s80
	s_addc_u32 s83, s43, 0
	global_load_ushort v19, v142, s[82:83] offset:3712
	s_add_i32 s80, s73, 5
	s_mul_i32 s80, s80, 0x1800
	s_add_u32 s82, s42, s80
	s_addc_u32 s83, s43, 0
	global_load_ushort v20, v142, s[82:83] offset:3712
	s_add_i32 s80, s73, 6
	s_mul_i32 s80, s80, 0x1800
	s_add_u32 s82, s42, s80
	s_addc_u32 s83, s43, 0
	global_load_ushort v21, v142, s[82:83] offset:3712
	s_add_i32 s80, s73, 7
	s_mul_i32 s80, s80, 0x1800
	s_add_u32 s82, s42, s80
	s_addc_u32 s83, s43, 0
	global_load_ushort v22, v142, s[82:83] offset:3712
	s_add_i32 s80, s73, 8
	s_mul_i32 s80, s80, 0x1800
	s_add_u32 s82, s42, s80
	s_addc_u32 s83, s43, 0
	global_load_ushort v23, v142, s[82:83] offset:3712
	s_add_i32 s80, s73, 9
	s_mul_i32 s80, s80, 0x1800
	s_add_u32 s82, s42, s80
	s_addc_u32 s83, s43, 0
	global_load_ushort v24, v142, s[82:83] offset:3712
	s_add_i32 s80, s73, 10
	s_mul_i32 s80, s80, 0x1800
	s_add_u32 s82, s42, s80
	s_addc_u32 s83, s43, 0
	global_load_ushort v25, v142, s[82:83] offset:3712
	s_add_i32 s80, s73, 11
	s_mul_i32 s80, s80, 0x1800
	s_add_u32 s82, s42, s80
	s_addc_u32 s83, s43, 0
	global_load_ushort v26, v142, s[82:83] offset:3712
	s_add_i32 s80, s73, 12
	s_mul_i32 s80, s80, 0x1800
	s_add_u32 s82, s42, s80
	s_addc_u32 s83, s43, 0
	global_load_ushort v27, v142, s[82:83] offset:3712
	s_add_i32 s80, s73, 13
	s_mul_i32 s80, s80, 0x1800
	s_add_u32 s82, s42, s80
	s_addc_u32 s83, s43, 0
	global_load_ushort v28, v142, s[82:83] offset:3712
	s_add_i32 s80, s73, 14
	s_mul_i32 s80, s80, 0x1800
	s_add_u32 s82, s42, s80
	s_addc_u32 s83, s43, 0
	global_load_ushort v29, v142, s[82:83] offset:3712
	s_add_i32 s80, s73, 15
	s_mul_i32 s80, s80, 0x1800
	s_add_u32 s82, s42, s80
	s_addc_u32 s83, s43, 0
	global_load_ushort v30, v142, s[82:83] offset:3712
	s_add_i32 s80, s73, 16
	s_min_i32 s80, s80, s75
	s_mul_i32 s80, s80, 0x1800
	s_add_u32 s82, s42, s80
	s_addc_u32 s83, s43, 0
	global_load_ushort v31, v142, s[82:83] offset:3712
	s_add_i32 s80, s73, 17
	s_min_i32 s80, s80, s75
	s_mul_i32 s80, s80, 0x1800
	s_add_u32 s82, s42, s80
	s_addc_u32 s83, s43, 0
	global_load_ushort v32, v142, s[82:83] offset:3712
	s_add_i32 s80, s73, 18
	s_min_i32 s80, s80, s75
	s_mul_i32 s80, s80, 0x1800
	s_add_u32 s82, s42, s80
	s_addc_u32 s83, s43, 0
	global_load_ushort v33, v142, s[82:83] offset:3712
	s_add_i32 s80, s73, 19
	s_min_i32 s80, s80, s75
	s_mul_i32 s80, s80, 0x1800
	s_add_u32 s82, s42, s80
	s_addc_u32 s83, s43, 0
	global_load_ushort v34, v142, s[82:83] offset:3712
	s_add_i32 s80, s73, 20
	s_min_i32 s80, s80, s75
	s_mul_i32 s80, s80, 0x1800
	s_add_u32 s82, s42, s80
	s_addc_u32 s83, s43, 0
	global_load_ushort v35, v142, s[82:83] offset:3712
	s_add_i32 s80, s73, 21
	s_min_i32 s80, s80, s75
	s_mul_i32 s80, s80, 0x1800
	s_add_u32 s82, s42, s80
	s_addc_u32 s83, s43, 0
	global_load_ushort v36, v142, s[82:83] offset:3712
	s_add_i32 s80, s73, 22
	s_min_i32 s80, s80, s75
	s_mul_i32 s80, s80, 0x1800
	s_add_u32 s82, s42, s80
	s_addc_u32 s83, s43, 0
	global_load_ushort v37, v142, s[82:83] offset:3712
	s_add_i32 s80, s73, 23
	s_min_i32 s80, s80, s75
	s_mul_i32 s80, s80, 0x1800
	s_add_u32 s82, s42, s80
	s_addc_u32 s83, s43, 0
	global_load_ushort v38, v142, s[82:83] offset:3712
	s_add_i32 s80, s73, 24
	s_min_i32 s80, s80, s75
	s_mul_i32 s80, s80, 0x1800
	s_add_u32 s82, s42, s80
	s_addc_u32 s83, s43, 0
	global_load_ushort v39, v142, s[82:83] offset:3712
	s_add_i32 s80, s73, 25
	s_min_i32 s80, s80, s75
	s_mul_i32 s80, s80, 0x1800
	s_add_u32 s82, s42, s80
	s_addc_u32 s83, s43, 0
	global_load_ushort v40, v142, s[82:83] offset:3712
	s_add_i32 s80, s73, 26
	s_min_i32 s80, s80, s75
	s_mul_i32 s80, s80, 0x1800
	s_add_u32 s82, s42, s80
	s_addc_u32 s83, s43, 0
	global_load_ushort v41, v142, s[82:83] offset:3712
	s_add_i32 s80, s73, 27
	s_min_i32 s80, s80, s75
	s_mul_i32 s80, s80, 0x1800
	s_add_u32 s82, s42, s80
	s_addc_u32 s83, s43, 0
	global_load_ushort v42, v142, s[82:83] offset:3712
	s_add_i32 s80, s73, 28
	s_min_i32 s80, s80, s75
	s_mul_i32 s80, s80, 0x1800
	s_add_u32 s82, s42, s80
	s_addc_u32 s83, s43, 0
	global_load_ushort v43, v142, s[82:83] offset:3712
	s_add_i32 s80, s73, 29
	s_min_i32 s80, s80, s75
	s_mul_i32 s80, s80, 0x1800
	s_add_u32 s82, s42, s80
	s_addc_u32 s83, s43, 0
	global_load_ushort v44, v142, s[82:83] offset:3712
	s_add_i32 s80, s73, 30
	s_min_i32 s80, s80, s75
	s_mul_i32 s80, s80, 0x1800
	s_add_u32 s82, s42, s80
	s_addc_u32 s83, s43, 0
	global_load_ushort v45, v142, s[82:83] offset:3712
	v_mov_b32_e32 v126, v123
	v_mov_b32_e32 v127, v123
	v_mov_b32_e32 v128, v123
	v_mov_b32_e32 v129, v123
	v_mov_b32_e32 v130, v123
	v_mov_b32_e32 v131, v123
	v_mov_b32_e32 v132, v123
	v_mov_b32_e32 v133, v123
	v_mov_b32_e32 v134, v123
	v_mov_b32_e32 v135, v123
	v_mov_b32_e32 v136, v123
	v_mov_b32_e32 v137, v123
	v_mov_b32_e32 v138, v123
	v_mov_b32_e32 v139, v123
	v_mov_b32_e32 v140, v123
	v_mov_b32_e32 v141, v123
	v_fmac_f32_e32 v126, v92, v46
	v_fmac_f32_e32 v126, v93, v47
	v_fmac_f32_e32 v127, v92, v47
	v_fmac_f32_e32 v126, v94, v48
	v_fmac_f32_e32 v127, v93, v48
	v_fmac_f32_e32 v128, v92, v48
	v_fmac_f32_e32 v126, v95, v49
	v_fmac_f32_e32 v127, v94, v49
	v_fmac_f32_e32 v128, v93, v49
	v_fmac_f32_e32 v129, v92, v49
	v_fmac_f32_e32 v126, v96, v50
	v_fmac_f32_e32 v127, v95, v50
	v_fmac_f32_e32 v128, v94, v50
	v_fmac_f32_e32 v129, v93, v50
	v_fmac_f32_e32 v130, v92, v50
	v_fmac_f32_e32 v126, v97, v51
	v_fmac_f32_e32 v127, v96, v51
	v_fmac_f32_e32 v128, v95, v51
	v_fmac_f32_e32 v129, v94, v51
	v_fmac_f32_e32 v130, v93, v51
	v_fmac_f32_e32 v131, v92, v51
	v_fmac_f32_e32 v126, v98, v52
	v_fmac_f32_e32 v127, v97, v52
	v_fmac_f32_e32 v128, v96, v52
	v_fmac_f32_e32 v129, v95, v52
	v_fmac_f32_e32 v130, v94, v52
	v_fmac_f32_e32 v131, v93, v52
	v_fmac_f32_e32 v132, v92, v52
	v_fmac_f32_e32 v126, v99, v53
	v_fmac_f32_e32 v127, v98, v53
	v_fmac_f32_e32 v128, v97, v53
	v_fmac_f32_e32 v129, v96, v53
	v_fmac_f32_e32 v130, v95, v53
	v_fmac_f32_e32 v131, v94, v53
	v_fmac_f32_e32 v132, v93, v53
	v_fmac_f32_e32 v133, v92, v53
	v_fmac_f32_e32 v126, v100, v54
	v_fmac_f32_e32 v127, v99, v54
	v_fmac_f32_e32 v128, v98, v54
	v_fmac_f32_e32 v129, v97, v54
	v_fmac_f32_e32 v130, v96, v54
	v_fmac_f32_e32 v131, v95, v54
	v_fmac_f32_e32 v132, v94, v54
	v_fmac_f32_e32 v133, v93, v54
	v_fmac_f32_e32 v134, v92, v54
	v_fmac_f32_e32 v126, v101, v55
	v_fmac_f32_e32 v127, v100, v55
	v_fmac_f32_e32 v128, v99, v55
	v_fmac_f32_e32 v129, v98, v55
	v_fmac_f32_e32 v130, v97, v55
	v_fmac_f32_e32 v131, v96, v55
	v_fmac_f32_e32 v132, v95, v55
	v_fmac_f32_e32 v133, v94, v55
	v_fmac_f32_e32 v134, v93, v55
	v_fmac_f32_e32 v135, v92, v55
	v_fmac_f32_e32 v126, v102, v56
	v_fmac_f32_e32 v127, v101, v56
	v_fmac_f32_e32 v128, v100, v56
	v_fmac_f32_e32 v129, v99, v56
	v_fmac_f32_e32 v130, v98, v56
	v_fmac_f32_e32 v131, v97, v56
	v_fmac_f32_e32 v132, v96, v56
	v_fmac_f32_e32 v133, v95, v56
	v_fmac_f32_e32 v134, v94, v56
	v_fmac_f32_e32 v135, v93, v56
	v_fmac_f32_e32 v136, v92, v56
	v_fmac_f32_e32 v126, v103, v57
	v_fmac_f32_e32 v127, v102, v57
	v_fmac_f32_e32 v128, v101, v57
	v_fmac_f32_e32 v129, v100, v57
	v_fmac_f32_e32 v130, v99, v57
	v_fmac_f32_e32 v131, v98, v57
	v_fmac_f32_e32 v132, v97, v57
	v_fmac_f32_e32 v133, v96, v57
	v_fmac_f32_e32 v134, v95, v57
	v_fmac_f32_e32 v135, v94, v57
	v_fmac_f32_e32 v136, v93, v57
	v_fmac_f32_e32 v137, v92, v57
	v_fmac_f32_e32 v126, v104, v58
	v_fmac_f32_e32 v127, v103, v58
	v_fmac_f32_e32 v128, v102, v58
	v_fmac_f32_e32 v129, v101, v58
	v_fmac_f32_e32 v130, v100, v58
	v_fmac_f32_e32 v131, v99, v58
	v_fmac_f32_e32 v132, v98, v58
	v_fmac_f32_e32 v133, v97, v58
	v_fmac_f32_e32 v134, v96, v58
	v_fmac_f32_e32 v135, v95, v58
	v_fmac_f32_e32 v136, v94, v58
	v_fmac_f32_e32 v137, v93, v58
	v_fmac_f32_e32 v138, v92, v58
	v_fmac_f32_e32 v126, v105, v59
	v_fmac_f32_e32 v127, v104, v59
	v_fmac_f32_e32 v128, v103, v59
	v_fmac_f32_e32 v129, v102, v59
	v_fmac_f32_e32 v130, v101, v59
	v_fmac_f32_e32 v131, v100, v59
	v_fmac_f32_e32 v132, v99, v59
	v_fmac_f32_e32 v133, v98, v59
	v_fmac_f32_e32 v134, v97, v59
	v_fmac_f32_e32 v135, v96, v59
	v_fmac_f32_e32 v136, v95, v59
	v_fmac_f32_e32 v137, v94, v59
	v_fmac_f32_e32 v138, v93, v59
	v_fmac_f32_e32 v139, v92, v59
	v_fmac_f32_e32 v126, v106, v60
	v_fmac_f32_e32 v127, v105, v60
	v_fmac_f32_e32 v128, v104, v60
	v_fmac_f32_e32 v129, v103, v60
	v_fmac_f32_e32 v130, v102, v60
	v_fmac_f32_e32 v131, v101, v60
	v_fmac_f32_e32 v132, v100, v60
	v_fmac_f32_e32 v133, v99, v60
	v_fmac_f32_e32 v134, v98, v60
	v_fmac_f32_e32 v135, v97, v60
	v_fmac_f32_e32 v136, v96, v60
	v_fmac_f32_e32 v137, v95, v60
	v_fmac_f32_e32 v138, v94, v60
	v_fmac_f32_e32 v139, v93, v60
	v_fmac_f32_e32 v140, v92, v60
	v_fmac_f32_e32 v126, v107, v61
	v_fmac_f32_e32 v127, v106, v61
	v_fmac_f32_e32 v128, v105, v61
	v_fmac_f32_e32 v129, v104, v61
	v_fmac_f32_e32 v130, v103, v61
	v_fmac_f32_e32 v131, v102, v61
	v_fmac_f32_e32 v132, v101, v61
	v_fmac_f32_e32 v133, v100, v61
	v_fmac_f32_e32 v134, v99, v61
	v_fmac_f32_e32 v135, v98, v61
	v_fmac_f32_e32 v136, v97, v61
	v_fmac_f32_e32 v137, v96, v61
	v_fmac_f32_e32 v138, v95, v61
	v_fmac_f32_e32 v139, v94, v61
	v_fmac_f32_e32 v140, v93, v61
	v_fmac_f32_e32 v141, v92, v61
	v_fmac_f32_e32 v126, v108, v62
	v_fmac_f32_e32 v127, v107, v62
	v_fmac_f32_e32 v128, v106, v62
	v_fmac_f32_e32 v129, v105, v62
	v_fmac_f32_e32 v130, v104, v62
	v_fmac_f32_e32 v131, v103, v62
	v_fmac_f32_e32 v132, v102, v62
	v_fmac_f32_e32 v133, v101, v62
	v_fmac_f32_e32 v134, v100, v62
	v_fmac_f32_e32 v135, v99, v62
	v_fmac_f32_e32 v136, v98, v62
	v_fmac_f32_e32 v137, v97, v62
	v_fmac_f32_e32 v138, v96, v62
	v_fmac_f32_e32 v139, v95, v62
	v_fmac_f32_e32 v140, v94, v62
	v_fmac_f32_e32 v141, v93, v62
	v_fmac_f32_e32 v126, v109, v63
	v_fmac_f32_e32 v127, v108, v63
	v_fmac_f32_e32 v128, v107, v63
	v_fmac_f32_e32 v129, v106, v63
	v_fmac_f32_e32 v130, v105, v63
	v_fmac_f32_e32 v131, v104, v63
	v_fmac_f32_e32 v132, v103, v63
	v_fmac_f32_e32 v133, v102, v63
	v_fmac_f32_e32 v134, v101, v63
	v_fmac_f32_e32 v135, v100, v63
	v_fmac_f32_e32 v136, v99, v63
	v_fmac_f32_e32 v137, v98, v63
	v_fmac_f32_e32 v138, v97, v63
	v_fmac_f32_e32 v139, v96, v63
	v_fmac_f32_e32 v140, v95, v63
	v_fmac_f32_e32 v141, v94, v63
	v_fmac_f32_e32 v126, v110, v64
	v_fmac_f32_e32 v127, v109, v64
	v_fmac_f32_e32 v128, v108, v64
	v_fmac_f32_e32 v129, v107, v64
	v_fmac_f32_e32 v130, v106, v64
	v_fmac_f32_e32 v131, v105, v64
	v_fmac_f32_e32 v132, v104, v64
	v_fmac_f32_e32 v133, v103, v64
	v_fmac_f32_e32 v134, v102, v64
	v_fmac_f32_e32 v135, v101, v64
	v_fmac_f32_e32 v136, v100, v64
	v_fmac_f32_e32 v137, v99, v64
	v_fmac_f32_e32 v138, v98, v64
	v_fmac_f32_e32 v139, v97, v64
	v_fmac_f32_e32 v140, v96, v64
	v_fmac_f32_e32 v141, v95, v64
	v_fmac_f32_e32 v126, v111, v65
	v_fmac_f32_e32 v127, v110, v65
	v_fmac_f32_e32 v128, v109, v65
	v_fmac_f32_e32 v129, v108, v65
	v_fmac_f32_e32 v130, v107, v65
	v_fmac_f32_e32 v131, v106, v65
	v_fmac_f32_e32 v132, v105, v65
	v_fmac_f32_e32 v133, v104, v65
	v_fmac_f32_e32 v134, v103, v65
	v_fmac_f32_e32 v135, v102, v65
	v_fmac_f32_e32 v136, v101, v65
	v_fmac_f32_e32 v137, v100, v65
	v_fmac_f32_e32 v138, v99, v65
	v_fmac_f32_e32 v139, v98, v65
	v_fmac_f32_e32 v140, v97, v65
	v_fmac_f32_e32 v141, v96, v65
	v_fmac_f32_e32 v126, v112, v66
	v_fmac_f32_e32 v127, v111, v66
	v_fmac_f32_e32 v128, v110, v66
	v_fmac_f32_e32 v129, v109, v66
	v_fmac_f32_e32 v130, v108, v66
	v_fmac_f32_e32 v131, v107, v66
	v_fmac_f32_e32 v132, v106, v66
	v_fmac_f32_e32 v133, v105, v66
	v_fmac_f32_e32 v134, v104, v66
	v_fmac_f32_e32 v135, v103, v66
	v_fmac_f32_e32 v136, v102, v66
	v_fmac_f32_e32 v137, v101, v66
	v_fmac_f32_e32 v138, v100, v66
	v_fmac_f32_e32 v139, v99, v66
	v_fmac_f32_e32 v140, v98, v66
	v_fmac_f32_e32 v141, v97, v66
	v_fmac_f32_e32 v126, v113, v67
	v_fmac_f32_e32 v127, v112, v67
	v_fmac_f32_e32 v128, v111, v67
	v_fmac_f32_e32 v129, v110, v67
	v_fmac_f32_e32 v130, v109, v67
	v_fmac_f32_e32 v131, v108, v67
	v_fmac_f32_e32 v132, v107, v67
	v_fmac_f32_e32 v133, v106, v67
	v_fmac_f32_e32 v134, v105, v67
	v_fmac_f32_e32 v135, v104, v67
	v_fmac_f32_e32 v136, v103, v67
	v_fmac_f32_e32 v137, v102, v67
	v_fmac_f32_e32 v138, v101, v67
	v_fmac_f32_e32 v139, v100, v67
	v_fmac_f32_e32 v140, v99, v67
	v_fmac_f32_e32 v141, v98, v67
	v_fmac_f32_e32 v126, v114, v68
	v_fmac_f32_e32 v127, v113, v68
	v_fmac_f32_e32 v128, v112, v68
	v_fmac_f32_e32 v129, v111, v68
	v_fmac_f32_e32 v130, v110, v68
	v_fmac_f32_e32 v131, v109, v68
	v_fmac_f32_e32 v132, v108, v68
	v_fmac_f32_e32 v133, v107, v68
	v_fmac_f32_e32 v134, v106, v68
	v_fmac_f32_e32 v135, v105, v68
	v_fmac_f32_e32 v136, v104, v68
	v_fmac_f32_e32 v137, v103, v68
	v_fmac_f32_e32 v138, v102, v68
	v_fmac_f32_e32 v139, v101, v68
	v_fmac_f32_e32 v140, v100, v68
	v_fmac_f32_e32 v141, v99, v68
	v_fmac_f32_e32 v126, v115, v69
	v_fmac_f32_e32 v127, v114, v69
	v_fmac_f32_e32 v128, v113, v69
	v_fmac_f32_e32 v129, v112, v69
	v_fmac_f32_e32 v130, v111, v69
	v_fmac_f32_e32 v131, v110, v69
	v_fmac_f32_e32 v132, v109, v69
	v_fmac_f32_e32 v133, v108, v69
	v_fmac_f32_e32 v134, v107, v69
	v_fmac_f32_e32 v135, v106, v69
	v_fmac_f32_e32 v136, v105, v69
	v_fmac_f32_e32 v137, v104, v69
	v_fmac_f32_e32 v138, v103, v69
	v_fmac_f32_e32 v139, v102, v69
	v_fmac_f32_e32 v140, v101, v69
	v_fmac_f32_e32 v141, v100, v69
	v_fmac_f32_e32 v126, v116, v70
	v_fmac_f32_e32 v127, v115, v70
	v_fmac_f32_e32 v128, v114, v70
	v_fmac_f32_e32 v129, v113, v70
	v_fmac_f32_e32 v130, v112, v70
	v_fmac_f32_e32 v131, v111, v70
	v_fmac_f32_e32 v132, v110, v70
	v_fmac_f32_e32 v133, v109, v70
	v_fmac_f32_e32 v134, v108, v70
	v_fmac_f32_e32 v135, v107, v70
	v_fmac_f32_e32 v136, v106, v70
	v_fmac_f32_e32 v137, v105, v70
	v_fmac_f32_e32 v138, v104, v70
	v_fmac_f32_e32 v139, v103, v70
	v_fmac_f32_e32 v140, v102, v70
	v_fmac_f32_e32 v141, v101, v70
	v_fmac_f32_e32 v126, v117, v71
	v_fmac_f32_e32 v127, v116, v71
	v_fmac_f32_e32 v128, v115, v71
	v_fmac_f32_e32 v129, v114, v71
	v_fmac_f32_e32 v130, v113, v71
	v_fmac_f32_e32 v131, v112, v71
	v_fmac_f32_e32 v132, v111, v71
	v_fmac_f32_e32 v133, v110, v71
	v_fmac_f32_e32 v134, v109, v71
	v_fmac_f32_e32 v135, v108, v71
	v_fmac_f32_e32 v136, v107, v71
	v_fmac_f32_e32 v137, v106, v71
	v_fmac_f32_e32 v138, v105, v71
	v_fmac_f32_e32 v139, v104, v71
	v_fmac_f32_e32 v140, v103, v71
	v_fmac_f32_e32 v141, v102, v71
	v_fmac_f32_e32 v126, v118, v72
	v_fmac_f32_e32 v127, v117, v72
	v_fmac_f32_e32 v128, v116, v72
	v_fmac_f32_e32 v129, v115, v72
	v_fmac_f32_e32 v130, v114, v72
	v_fmac_f32_e32 v131, v113, v72
	v_fmac_f32_e32 v132, v112, v72
	v_fmac_f32_e32 v133, v111, v72
	v_fmac_f32_e32 v134, v110, v72
	v_fmac_f32_e32 v135, v109, v72
	v_fmac_f32_e32 v136, v108, v72
	v_fmac_f32_e32 v137, v107, v72
	v_fmac_f32_e32 v138, v106, v72
	v_fmac_f32_e32 v139, v105, v72
	v_fmac_f32_e32 v140, v104, v72
	v_fmac_f32_e32 v141, v103, v72
	v_fmac_f32_e32 v126, v119, v73
	v_fmac_f32_e32 v127, v118, v73
	v_fmac_f32_e32 v128, v117, v73
	v_fmac_f32_e32 v129, v116, v73
	v_fmac_f32_e32 v130, v115, v73
	v_fmac_f32_e32 v131, v114, v73
	v_fmac_f32_e32 v132, v113, v73
	v_fmac_f32_e32 v133, v112, v73
	v_fmac_f32_e32 v134, v111, v73
	v_fmac_f32_e32 v135, v110, v73
	v_fmac_f32_e32 v136, v109, v73
	v_fmac_f32_e32 v137, v108, v73
	v_fmac_f32_e32 v138, v107, v73
	v_fmac_f32_e32 v139, v106, v73
	v_fmac_f32_e32 v140, v105, v73
	v_fmac_f32_e32 v141, v104, v73
	v_fmac_f32_e32 v126, v120, v74
	v_fmac_f32_e32 v127, v119, v74
	v_fmac_f32_e32 v128, v118, v74
	v_fmac_f32_e32 v129, v117, v74
	v_fmac_f32_e32 v130, v116, v74
	v_fmac_f32_e32 v131, v115, v74
	v_fmac_f32_e32 v132, v114, v74
	v_fmac_f32_e32 v133, v113, v74
	v_fmac_f32_e32 v134, v112, v74
	v_fmac_f32_e32 v135, v111, v74
	v_fmac_f32_e32 v136, v110, v74
	v_fmac_f32_e32 v137, v109, v74
	v_fmac_f32_e32 v138, v108, v74
	v_fmac_f32_e32 v139, v107, v74
	v_fmac_f32_e32 v140, v106, v74
	v_fmac_f32_e32 v141, v105, v74
	v_fmac_f32_e32 v126, v121, v75
	v_fmac_f32_e32 v127, v120, v75
	v_fmac_f32_e32 v128, v119, v75
	v_fmac_f32_e32 v129, v118, v75
	v_fmac_f32_e32 v130, v117, v75
	v_fmac_f32_e32 v131, v116, v75
	v_fmac_f32_e32 v132, v115, v75
	v_fmac_f32_e32 v133, v114, v75
	v_fmac_f32_e32 v134, v113, v75
	v_fmac_f32_e32 v135, v112, v75
	v_fmac_f32_e32 v136, v111, v75
	v_fmac_f32_e32 v137, v110, v75
	v_fmac_f32_e32 v138, v109, v75
	v_fmac_f32_e32 v139, v108, v75
	v_fmac_f32_e32 v140, v107, v75
	v_fmac_f32_e32 v141, v106, v75
	v_fmac_f32_e32 v126, v122, v76
	v_fmac_f32_e32 v127, v121, v76
	v_fmac_f32_e32 v128, v120, v76
	v_fmac_f32_e32 v129, v119, v76
	v_fmac_f32_e32 v130, v118, v76
	v_fmac_f32_e32 v131, v117, v76
	v_fmac_f32_e32 v132, v116, v76
	v_fmac_f32_e32 v133, v115, v76
	v_fmac_f32_e32 v134, v114, v76
	v_fmac_f32_e32 v135, v113, v76
	v_fmac_f32_e32 v136, v112, v76
	v_fmac_f32_e32 v137, v111, v76
	v_fmac_f32_e32 v138, v110, v76
	v_fmac_f32_e32 v139, v109, v76
	v_fmac_f32_e32 v140, v108, v76
	v_fmac_f32_e32 v141, v107, v76
	v_fmac_f32_e32 v127, v122, v77
	v_fmac_f32_e32 v128, v121, v77
	v_fmac_f32_e32 v129, v120, v77
	v_fmac_f32_e32 v130, v119, v77
	v_fmac_f32_e32 v131, v118, v77
	v_fmac_f32_e32 v132, v117, v77
	v_fmac_f32_e32 v133, v116, v77
	v_fmac_f32_e32 v134, v115, v77
	v_fmac_f32_e32 v135, v114, v77
	v_fmac_f32_e32 v136, v113, v77
	v_fmac_f32_e32 v137, v112, v77
	v_fmac_f32_e32 v138, v111, v77
	v_fmac_f32_e32 v139, v110, v77
	v_fmac_f32_e32 v140, v109, v77
	v_fmac_f32_e32 v141, v108, v77
	v_fmac_f32_e32 v128, v122, v78
	v_fmac_f32_e32 v129, v121, v78
	v_fmac_f32_e32 v130, v120, v78
	v_fmac_f32_e32 v131, v119, v78
	v_fmac_f32_e32 v132, v118, v78
	v_fmac_f32_e32 v133, v117, v78
	v_fmac_f32_e32 v134, v116, v78
	v_fmac_f32_e32 v135, v115, v78
	v_fmac_f32_e32 v136, v114, v78
	v_fmac_f32_e32 v137, v113, v78
	v_fmac_f32_e32 v138, v112, v78
	v_fmac_f32_e32 v139, v111, v78
	v_fmac_f32_e32 v140, v110, v78
	v_fmac_f32_e32 v141, v109, v78
	v_fmac_f32_e32 v129, v122, v79
	v_fmac_f32_e32 v130, v121, v79
	v_fmac_f32_e32 v131, v120, v79
	v_fmac_f32_e32 v132, v119, v79
	v_fmac_f32_e32 v133, v118, v79
	v_fmac_f32_e32 v134, v117, v79
	v_fmac_f32_e32 v135, v116, v79
	v_fmac_f32_e32 v136, v115, v79
	v_fmac_f32_e32 v137, v114, v79
	v_fmac_f32_e32 v138, v113, v79
	v_fmac_f32_e32 v139, v112, v79
	v_fmac_f32_e32 v140, v111, v79
	v_fmac_f32_e32 v141, v110, v79
	v_fmac_f32_e32 v130, v122, v80
	v_fmac_f32_e32 v131, v121, v80
	v_fmac_f32_e32 v132, v120, v80
	v_fmac_f32_e32 v133, v119, v80
	v_fmac_f32_e32 v134, v118, v80
	v_fmac_f32_e32 v135, v117, v80
	v_fmac_f32_e32 v136, v116, v80
	v_fmac_f32_e32 v137, v115, v80
	v_fmac_f32_e32 v138, v114, v80
	v_fmac_f32_e32 v139, v113, v80
	v_fmac_f32_e32 v140, v112, v80
	v_fmac_f32_e32 v141, v111, v80
	v_fmac_f32_e32 v131, v122, v81
	v_fmac_f32_e32 v132, v121, v81
	v_fmac_f32_e32 v133, v120, v81
	v_fmac_f32_e32 v134, v119, v81
	v_fmac_f32_e32 v135, v118, v81
	v_fmac_f32_e32 v136, v117, v81
	v_fmac_f32_e32 v137, v116, v81
	v_fmac_f32_e32 v138, v115, v81
	v_fmac_f32_e32 v139, v114, v81
	v_fmac_f32_e32 v140, v113, v81
	v_fmac_f32_e32 v141, v112, v81
	v_fmac_f32_e32 v132, v122, v82
	v_fmac_f32_e32 v133, v121, v82
	v_fmac_f32_e32 v134, v120, v82
	v_fmac_f32_e32 v135, v119, v82
	v_fmac_f32_e32 v136, v118, v82
	v_fmac_f32_e32 v137, v117, v82
	v_fmac_f32_e32 v138, v116, v82
	v_fmac_f32_e32 v139, v115, v82
	v_fmac_f32_e32 v140, v114, v82
	v_fmac_f32_e32 v141, v113, v82
	v_fmac_f32_e32 v133, v122, v83
	v_fmac_f32_e32 v134, v121, v83
	v_fmac_f32_e32 v135, v120, v83
	v_fmac_f32_e32 v136, v119, v83
	v_fmac_f32_e32 v137, v118, v83
	v_fmac_f32_e32 v138, v117, v83
	v_fmac_f32_e32 v139, v116, v83
	v_fmac_f32_e32 v140, v115, v83
	v_fmac_f32_e32 v141, v114, v83
	v_fmac_f32_e32 v134, v122, v84
	v_fmac_f32_e32 v135, v121, v84
	v_fmac_f32_e32 v136, v120, v84
	v_fmac_f32_e32 v137, v119, v84
	v_fmac_f32_e32 v138, v118, v84
	v_fmac_f32_e32 v139, v117, v84
	v_fmac_f32_e32 v140, v116, v84
	v_fmac_f32_e32 v141, v115, v84
	v_fmac_f32_e32 v135, v122, v85
	v_fmac_f32_e32 v136, v121, v85
	v_fmac_f32_e32 v137, v120, v85
	v_fmac_f32_e32 v138, v119, v85
	v_fmac_f32_e32 v139, v118, v85
	v_fmac_f32_e32 v140, v117, v85
	v_fmac_f32_e32 v141, v116, v85
	v_fmac_f32_e32 v136, v122, v86
	v_fmac_f32_e32 v137, v121, v86
	v_fmac_f32_e32 v138, v120, v86
	v_fmac_f32_e32 v139, v119, v86
	v_fmac_f32_e32 v140, v118, v86
	v_fmac_f32_e32 v141, v117, v86
	v_fmac_f32_e32 v137, v122, v87
	v_fmac_f32_e32 v138, v121, v87
	v_fmac_f32_e32 v139, v120, v87
	v_fmac_f32_e32 v140, v119, v87
	v_fmac_f32_e32 v141, v118, v87
	v_fmac_f32_e32 v138, v122, v88
	v_fmac_f32_e32 v139, v121, v88
	v_fmac_f32_e32 v140, v120, v88
	v_fmac_f32_e32 v141, v119, v88
	v_fmac_f32_e32 v139, v122, v89
	v_fmac_f32_e32 v140, v121, v89
	v_fmac_f32_e32 v141, v120, v89
	v_fmac_f32_e32 v140, v122, v90
	v_fmac_f32_e32 v141, v121, v90
	v_fmac_f32_e32 v141, v122, v91
	ds_write_b32 v143, v126
	ds_write_b32 v143, v127 offset:2048
	ds_write_b32 v143, v128 offset:4096
	ds_write_b32 v143, v129 offset:6144
	ds_write_b32 v143, v130 offset:8192
	ds_write_b32 v143, v131 offset:10240
	ds_write_b32 v143, v132 offset:12288
	ds_write_b32 v143, v133 offset:14336
	ds_write_b32 v143, v134 offset:16384
	ds_write_b32 v143, v135 offset:18432
	ds_write_b32 v143, v136 offset:20480
	ds_write_b32 v143, v137 offset:22528
	ds_write_b32 v143, v138 offset:24576
	ds_write_b32 v143, v139 offset:26624
	ds_write_b32 v143, v140 offset:28672
	ds_write_b32 v143, v141 offset:30720
	s_waitcnt lgkmcnt(0)
	s_barrier
	ds_read_b128 v[46:49], v144
	ds_read_b128 v[50:53], v144 offset:16
	ds_read_b128 v[54:57], v144 offset:32
	ds_read_b128 v[58:61], v144 offset:48
	s_waitcnt lgkmcnt(0)
	v_add_f32_e32 v152, v46, v47
	v_mul_f32_e32 v153, v46, v46
	v_fmac_f32_e32 v153, v47, v47
	v_add_f32_e32 v152, v152, v48
	v_fmac_f32_e32 v153, v48, v48
	v_add_f32_e32 v152, v152, v49
	v_fmac_f32_e32 v153, v49, v49
	v_add_f32_e32 v152, v152, v50
	v_fmac_f32_e32 v153, v50, v50
	v_add_f32_e32 v152, v152, v51
	v_fmac_f32_e32 v153, v51, v51
	v_add_f32_e32 v152, v152, v52
	v_fmac_f32_e32 v153, v52, v52
	v_add_f32_e32 v152, v152, v53
	v_fmac_f32_e32 v153, v53, v53
	v_add_f32_e32 v152, v152, v54
	v_fmac_f32_e32 v153, v54, v54
	v_add_f32_e32 v152, v152, v55
	v_fmac_f32_e32 v153, v55, v55
	v_add_f32_e32 v152, v152, v56
	v_fmac_f32_e32 v153, v56, v56
	v_add_f32_e32 v152, v152, v57
	v_fmac_f32_e32 v153, v57, v57
	v_add_f32_e32 v152, v152, v58
	v_fmac_f32_e32 v153, v58, v58
	v_add_f32_e32 v152, v152, v59
	v_fmac_f32_e32 v153, v59, v59
	v_add_f32_e32 v152, v152, v60
	v_fmac_f32_e32 v153, v60, v60
	v_add_f32_e32 v152, v152, v61
	v_fmac_f32_e32 v153, v61, v61
	ds_bpermute_b32 v154, v146, v152
	ds_bpermute_b32 v155, v146, v153
	s_waitcnt lgkmcnt(1)
	v_add_f32_e32 v152, v152, v154
	s_waitcnt lgkmcnt(0)
	v_add_f32_e32 v153, v153, v155
	ds_bpermute_b32 v154, v147, v152
	ds_bpermute_b32 v155, v147, v153
	s_waitcnt lgkmcnt(1)
	v_add_f32_e32 v152, v152, v154
	s_waitcnt lgkmcnt(0)
	v_add_f32_e32 v153, v153, v155
	ds_bpermute_b32 v154, v148, v152
	ds_bpermute_b32 v155, v148, v153
	s_waitcnt lgkmcnt(1)
	v_add_f32_e32 v152, v152, v154
	s_waitcnt lgkmcnt(0)
	v_add_f32_e32 v153, v153, v155
	ds_bpermute_b32 v154, v149, v152
	ds_bpermute_b32 v155, v149, v153
	s_waitcnt lgkmcnt(1)
	v_add_f32_e32 v152, v152, v154
	s_waitcnt lgkmcnt(0)
	v_add_f32_e32 v153, v153, v155
	ds_bpermute_b32 v154, v150, v152
	ds_bpermute_b32 v155, v150, v153
	s_waitcnt lgkmcnt(1)
	v_add_f32_e32 v152, v152, v154
	s_waitcnt lgkmcnt(0)
	v_add_f32_e32 v153, v153, v155
	v_mul_f32_e32 v152, 0x3b000000, v152
	v_mul_f32_e32 v153, 0x3b000000, v153
	v_fma_f32 v153, -v152, v152, v153
	v_max_f32_e32 v153, 0, v153
	v_add_f32_e32 v153, v173, v153
	v_rsq_f32_e32 v153, v153
	s_mov_b32 s80, 1
	s_mov_b32 s81, 1
	s_mov_b64 exec, s[80:81]
	ds_write_b64 v145, v[152:153]
	s_mov_b64 exec, -1
	s_waitcnt lgkmcnt(0)
	s_barrier
	ds_read_b128 v[46:49], v151
	ds_read_b128 v[50:53], v151 offset:16
	ds_read_b128 v[54:57], v151 offset:32
	ds_read_b128 v[58:61], v151 offset:48
	ds_read_b128 v[62:65], v151 offset:64
	ds_read_b128 v[66:69], v151 offset:80
	ds_read_b128 v[70:73], v151 offset:96
	ds_read_b128 v[74:77], v151 offset:112
	s_lshl_b32 s80, s70, 16
	s_add_u32 s82, s46, s80
	s_addc_u32 s83, s47, 0
	s_waitcnt lgkmcnt(0)
	v_sub_f32_e32 v126, v126, v46
	v_sub_f32_e32 v127, v127, v48
	v_mul_f32_e32 v126, v126, v47
	v_mul_f32_e32 v127, v127, v49
	v_fma_f32 v126, v126, v124, v125
	v_fma_f32 v127, v127, v124, v125
	v_mul_f32_e32 v152, 0xbfb8aa3b, v126
	v_mul_f32_e32 v153, 0xbfb8aa3b, v127
	v_exp_f32_e32 v152, v152
	v_exp_f32_e32 v153, v153
	s_nop 0
	v_add_f32_e32 v152, 1.0, v152
	v_add_f32_e32 v153, 1.0, v153
	v_rcp_f32_e32 v152, v152
	v_rcp_f32_e32 v153, v153
	s_nop 0
	v_mul_f32_e32 v126, v126, v152
	v_mul_f32_e32 v127, v127, v153
	v_bfe_u32 v152, v126, 16, 1
	v_bfe_u32 v153, v127, 16, 1
	v_add3_u32 v126, v126, v152, s37
	v_add3_u32 v127, v127, v153, s37
	global_store_short_d16_hi v142, v126, s[82:83] offset:3072
	s_add_u32 s82, s82, 0x1000
	s_addc_u32 s83, s83, 0
	global_store_short_d16_hi v142, v127, s[82:83] offset:3072
	s_add_u32 s82, s82, 0x1000
	s_addc_u32 s83, s83, 0
	v_sub_f32_e32 v128, v128, v50
	v_sub_f32_e32 v129, v129, v52
	v_mul_f32_e32 v128, v128, v51
	v_mul_f32_e32 v129, v129, v53
	v_fma_f32 v128, v128, v124, v125
	v_fma_f32 v129, v129, v124, v125
	v_mul_f32_e32 v152, 0xbfb8aa3b, v128
	v_mul_f32_e32 v153, 0xbfb8aa3b, v129
	v_exp_f32_e32 v152, v152
	v_exp_f32_e32 v153, v153
	s_nop 0
	v_add_f32_e32 v152, 1.0, v152
	v_add_f32_e32 v153, 1.0, v153
	v_rcp_f32_e32 v152, v152
	v_rcp_f32_e32 v153, v153
	s_nop 0
	v_mul_f32_e32 v128, v128, v152
	v_mul_f32_e32 v129, v129, v153
	v_bfe_u32 v152, v128, 16, 1
	v_bfe_u32 v153, v129, 16, 1
	v_add3_u32 v128, v128, v152, s37
	v_add3_u32 v129, v129, v153, s37
	global_store_short_d16_hi v142, v128, s[82:83] offset:3072
	s_add_u32 s82, s82, 0x1000
	s_addc_u32 s83, s83, 0
	global_store_short_d16_hi v142, v129, s[82:83] offset:3072
	s_add_u32 s82, s82, 0x1000
	s_addc_u32 s83, s83, 0
	v_sub_f32_e32 v130, v130, v54
	v_sub_f32_e32 v131, v131, v56
	v_mul_f32_e32 v130, v130, v55
	v_mul_f32_e32 v131, v131, v57
	v_fma_f32 v130, v130, v124, v125
	v_fma_f32 v131, v131, v124, v125
	v_mul_f32_e32 v152, 0xbfb8aa3b, v130
	v_mul_f32_e32 v153, 0xbfb8aa3b, v131
	v_exp_f32_e32 v152, v152
	v_exp_f32_e32 v153, v153
	s_nop 0
	v_add_f32_e32 v152, 1.0, v152
	v_add_f32_e32 v153, 1.0, v153
	v_rcp_f32_e32 v152, v152
	v_rcp_f32_e32 v153, v153
	s_nop 0
	v_mul_f32_e32 v130, v130, v152
	v_mul_f32_e32 v131, v131, v153
	v_bfe_u32 v152, v130, 16, 1
	v_bfe_u32 v153, v131, 16, 1
	v_add3_u32 v130, v130, v152, s37
	v_add3_u32 v131, v131, v153, s37
	global_store_short_d16_hi v142, v130, s[82:83] offset:3072
	s_add_u32 s82, s82, 0x1000
	s_addc_u32 s83, s83, 0
	global_store_short_d16_hi v142, v131, s[82:83] offset:3072
	s_add_u32 s82, s82, 0x1000
	s_addc_u32 s83, s83, 0
	v_sub_f32_e32 v132, v132, v58
	v_sub_f32_e32 v133, v133, v60
	v_mul_f32_e32 v132, v132, v59
	v_mul_f32_e32 v133, v133, v61
	v_fma_f32 v132, v132, v124, v125
	v_fma_f32 v133, v133, v124, v125
	v_mul_f32_e32 v152, 0xbfb8aa3b, v132
	v_mul_f32_e32 v153, 0xbfb8aa3b, v133
	v_exp_f32_e32 v152, v152
	v_exp_f32_e32 v153, v153
	s_nop 0
	v_add_f32_e32 v152, 1.0, v152
	v_add_f32_e32 v153, 1.0, v153
	v_rcp_f32_e32 v152, v152
	v_rcp_f32_e32 v153, v153
	s_nop 0
	v_mul_f32_e32 v132, v132, v152
	v_mul_f32_e32 v133, v133, v153
	v_bfe_u32 v152, v132, 16, 1
	v_bfe_u32 v153, v133, 16, 1
	v_add3_u32 v132, v132, v152, s37
	v_add3_u32 v133, v133, v153, s37
	global_store_short_d16_hi v142, v132, s[82:83] offset:3072
	s_add_u32 s82, s82, 0x1000
	s_addc_u32 s83, s83, 0
	global_store_short_d16_hi v142, v133, s[82:83] offset:3072
	s_add_u32 s82, s82, 0x1000
	s_addc_u32 s83, s83, 0
	v_sub_f32_e32 v134, v134, v62
	v_sub_f32_e32 v135, v135, v64
	v_mul_f32_e32 v134, v134, v63
	v_mul_f32_e32 v135, v135, v65
	v_fma_f32 v134, v134, v124, v125
	v_fma_f32 v135, v135, v124, v125
	v_mul_f32_e32 v152, 0xbfb8aa3b, v134
	v_mul_f32_e32 v153, 0xbfb8aa3b, v135
	v_exp_f32_e32 v152, v152
	v_exp_f32_e32 v153, v153
	s_nop 0
	v_add_f32_e32 v152, 1.0, v152
	v_add_f32_e32 v153, 1.0, v153
	v_rcp_f32_e32 v152, v152
	v_rcp_f32_e32 v153, v153
	s_nop 0
	v_mul_f32_e32 v134, v134, v152
	v_mul_f32_e32 v135, v135, v153
	v_bfe_u32 v152, v134, 16, 1
	v_bfe_u32 v153, v135, 16, 1
	v_add3_u32 v134, v134, v152, s37
	v_add3_u32 v135, v135, v153, s37
	global_store_short_d16_hi v142, v134, s[82:83] offset:3072
	s_add_u32 s82, s82, 0x1000
	s_addc_u32 s83, s83, 0
	global_store_short_d16_hi v142, v135, s[82:83] offset:3072
	s_add_u32 s82, s82, 0x1000
	s_addc_u32 s83, s83, 0
	v_sub_f32_e32 v136, v136, v66
	v_sub_f32_e32 v137, v137, v68
	v_mul_f32_e32 v136, v136, v67
	v_mul_f32_e32 v137, v137, v69
	v_fma_f32 v136, v136, v124, v125
	v_fma_f32 v137, v137, v124, v125
	v_mul_f32_e32 v152, 0xbfb8aa3b, v136
	v_mul_f32_e32 v153, 0xbfb8aa3b, v137
	v_exp_f32_e32 v152, v152
	v_exp_f32_e32 v153, v153
	s_nop 0
	v_add_f32_e32 v152, 1.0, v152
	v_add_f32_e32 v153, 1.0, v153
	v_rcp_f32_e32 v152, v152
	v_rcp_f32_e32 v153, v153
	s_nop 0
	v_mul_f32_e32 v136, v136, v152
	v_mul_f32_e32 v137, v137, v153
	v_bfe_u32 v152, v136, 16, 1
	v_bfe_u32 v153, v137, 16, 1
	v_add3_u32 v136, v136, v152, s37
	v_add3_u32 v137, v137, v153, s37
	global_store_short_d16_hi v142, v136, s[82:83] offset:3072
	s_add_u32 s82, s82, 0x1000
	s_addc_u32 s83, s83, 0
	global_store_short_d16_hi v142, v137, s[82:83] offset:3072
	s_add_u32 s82, s82, 0x1000
	s_addc_u32 s83, s83, 0
	v_sub_f32_e32 v138, v138, v70
	v_sub_f32_e32 v139, v139, v72
	v_mul_f32_e32 v138, v138, v71
	v_mul_f32_e32 v139, v139, v73
	v_fma_f32 v138, v138, v124, v125
	v_fma_f32 v139, v139, v124, v125
	v_mul_f32_e32 v152, 0xbfb8aa3b, v138
	v_mul_f32_e32 v153, 0xbfb8aa3b, v139
	v_exp_f32_e32 v152, v152
	v_exp_f32_e32 v153, v153
	s_nop 0
	v_add_f32_e32 v152, 1.0, v152
	v_add_f32_e32 v153, 1.0, v153
	v_rcp_f32_e32 v152, v152
	v_rcp_f32_e32 v153, v153
	s_nop 0
	v_mul_f32_e32 v138, v138, v152
	v_mul_f32_e32 v139, v139, v153
	v_bfe_u32 v152, v138, 16, 1
	v_bfe_u32 v153, v139, 16, 1
	v_add3_u32 v138, v138, v152, s37
	v_add3_u32 v139, v139, v153, s37
	global_store_short_d16_hi v142, v138, s[82:83] offset:3072
	s_add_u32 s82, s82, 0x1000
	s_addc_u32 s83, s83, 0
	global_store_short_d16_hi v142, v139, s[82:83] offset:3072
	s_add_u32 s82, s82, 0x1000
	s_addc_u32 s83, s83, 0
	v_sub_f32_e32 v140, v140, v74
	v_sub_f32_e32 v141, v141, v76
	v_mul_f32_e32 v140, v140, v75
	v_mul_f32_e32 v141, v141, v77
	v_fma_f32 v140, v140, v124, v125
	v_fma_f32 v141, v141, v124, v125
	v_mul_f32_e32 v152, 0xbfb8aa3b, v140
	v_mul_f32_e32 v153, 0xbfb8aa3b, v141
	v_exp_f32_e32 v152, v152
	v_exp_f32_e32 v153, v153
	s_nop 0
	v_add_f32_e32 v152, 1.0, v152
	v_add_f32_e32 v153, 1.0, v153
	v_rcp_f32_e32 v152, v152
	v_rcp_f32_e32 v153, v153
	s_nop 0
	v_mul_f32_e32 v140, v140, v152
	v_mul_f32_e32 v141, v141, v153
	v_bfe_u32 v152, v140, 16, 1
	v_bfe_u32 v153, v141, 16, 1
	v_add3_u32 v140, v140, v152, s37
	v_add3_u32 v141, v141, v153, s37
	global_store_short_d16_hi v142, v140, s[82:83] offset:3072
	s_add_u32 s82, s82, 0x1000
	s_addc_u32 s83, s83, 0
	global_store_short_d16_hi v142, v141, s[82:83] offset:3072
	s_add_u32 s82, s82, 0x1000
	s_addc_u32 s83, s83, 0
	s_add_i32 s70, s70, s34
	s_cmp_lt_i32 s70, s71
	s_cbranch_scc1 .Lconv_loop
	s_waitcnt vmcnt(0)
	s_waitcnt lgkmcnt(0)
	s_barrier
	s_branch .LBB0_705
